# mix3 gated-RMSNorm loads batched before first wait + DeltaNet forward-substitution LDS reads prefetched (register renaming), numerics unchanged
# speedup vs baseline: 1.0103x; 1.0103x over previous
.LBB0_809:
	v_readlane_b32 s6, v253, 34
	s_waitcnt lgkmcnt(0)
	s_barrier
	v_mov_b32_e32 v5, s6
	ds_read_b128 v[146:149], v5 offset:18688
	ds_read_b128 v[150:153], v5 offset:18944
	ds_read_b128 v[178:181], v5 offset:19200
	ds_read_b128 v[182:185], v5 offset:19456
	ds_read_b128 v[186:189], v5 offset:19712
	ds_read_b128 v[190:193], v5 offset:19728
	ds_read_b128 v[194:197], v5 offset:19968
	ds_read_b128 v[198:201], v5 offset:19984
	ds_read_b128 v[202:205], v5 offset:20224
	ds_read_b128 v[206:209], v5 offset:20240
	ds_read_b128 v[214:217], v5 offset:20480
	ds_read_b128 v[228:231], v5 offset:20496
	s_waitcnt lgkmcnt(11)
	v_fma_f32 v0, -v60, v146, v61
	v_fma_f32 v0, -v61, v147, v0
	v_fma_f32 v0, -v82, v148, v0
	v_fma_f32 v0, -v83, v149, v0
	ds_read_b128 v[232:235], v5 offset:20736
	s_waitcnt lgkmcnt(11)
	v_fma_f32 v1, -v60, v150, v82
	v_fma_f32 v1, -v151, v0, v1
	v_fma_f32 v1, -v82, v152, v1
	v_fma_f32 v1, -v83, v153, v1
	ds_read_b128 v[244:247], v5 offset:20752
	s_waitcnt lgkmcnt(11)
	v_fma_f32 v2, -v60, v178, v83
	v_fma_f32 v2, -v179, v0, v2
	v_fma_f32 v2, -v180, v1, v2
	v_fma_f32 v2, -v83, v181, v2
	ds_read_b128 v[146:149], v5 offset:20768
	s_waitcnt lgkmcnt(11)
	v_fma_f32 v3, -v60, v182, v86
	v_fma_f32 v3, -v183, v0, v3
	v_fma_f32 v3, -v184, v1, v3
	v_fma_f32 v3, -v185, v2, v3
	ds_read_b128 v[150:153], v5 offset:20992
	s_waitcnt lgkmcnt(11)
	v_fma_f32 v4, -v60, v186, v87
	v_fma_f32 v4, -v187, v0, v4
	v_fma_f32 v4, -v188, v1, v4
	v_fma_f32 v4, -v189, v2, v4
	ds_read_b128 v[178:181], v5 offset:21008
	s_waitcnt lgkmcnt(11)
	v_fma_f32 v4, -v190, v3, v4
	v_fma_f32 v4, -v87, v191, v4
	v_fma_f32 v4, -v80, v192, v4
	v_fma_f32 v4, -v81, v193, v4
	ds_read_b128 v[182:185], v5 offset:21024
	s_waitcnt lgkmcnt(11)
	v_fma_f32 v6, -v60, v194, v80
	v_fma_f32 v6, -v0, v195, v6
	v_fma_f32 v6, -v196, v1, v6
	v_fma_f32 v10, -v197, v2, v6
	ds_read_b128 v[186:189], v5 offset:21248
	s_waitcnt lgkmcnt(11)
	v_fma_f32 v6, -v198, v3, v10
	v_fma_f32 v6, -v199, v4, v6
	v_fma_f32 v6, -v80, v200, v6
	v_fma_f32 v6, -v81, v201, v6
	ds_read_b128 v[190:193], v5 offset:21264
	s_waitcnt lgkmcnt(11)
	v_fma_f32 v7, -v60, v202, v81
	v_fma_f32 v7, -v0, v203, v7
	v_fma_f32 v7, -v204, v1, v7
	v_fma_f32 v7, -v205, v2, v7
	ds_read_b128 v[194:197], v5 offset:21280
	s_waitcnt lgkmcnt(11)
	v_fma_f32 v7, -v206, v3, v7
	v_fma_f32 v7, -v207, v4, v7
	v_fma_f32 v7, -v208, v6, v7
	v_fma_f32 v7, -v81, v209, v7
	ds_read_b128 v[198:201], v5 offset:21504
	s_waitcnt lgkmcnt(11)
	v_fma_f32 v8, -v60, v214, v72
	v_fma_f32 v8, -v0, v215, v8
	v_fma_f32 v8, -v1, v216, v8
	v_fma_f32 v12, -v217, v2, v8
	ds_read_b128 v[202:205], v5 offset:21520
	s_waitcnt lgkmcnt(11)
	v_fma_f32 v8, -v228, v3, v12
	v_fma_f32 v8, -v229, v4, v8
	v_fma_f32 v8, -v230, v6, v8
	v_fma_f32 v8, -v231, v7, v8
	ds_read_b128 v[206:209], v5 offset:21536
	s_waitcnt lgkmcnt(11)
	v_fma_f32 v9, -v60, v232, v73
	v_fma_f32 v9, -v0, v233, v9
	v_fma_f32 v9, -v1, v234, v9
	v_fma_f32 v9, -v235, v2, v9
	ds_read_b128 v[214:217], v5 offset:21760
	s_waitcnt lgkmcnt(11)
	v_fma_f32 v9, -v244, v3, v9
	v_fma_f32 v9, -v245, v4, v9
	v_fma_f32 v9, -v246, v6, v9
	v_fma_f32 v9, -v247, v7, v9
	ds_read_b128 v[228:231], v5 offset:21776
	s_waitcnt lgkmcnt(11)
	v_fma_f32 v9, -v146, v8, v9
	v_fma_f32 v9, -v73, v147, v9
	v_fma_f32 v9, -v54, v148, v9
	v_fma_f32 v9, -v55, v149, v9
	ds_read_b128 v[232:235], v5 offset:21792
	s_waitcnt lgkmcnt(11)
	v_fma_f32 v10, -v60, v150, v54
	v_fma_f32 v10, -v0, v151, v10
	v_fma_f32 v10, -v1, v152, v10
	v_fma_f32 v14, -v2, v153, v10
	ds_read_b128 v[244:247], v5 offset:21808
	s_waitcnt lgkmcnt(11)
	v_fma_f32 v10, -v3, v178, v14
	v_fma_f32 v10, -v179, v4, v10
	v_fma_f32 v10, -v180, v6, v10
	v_fma_f32 v14, -v181, v7, v10
	ds_read_b128 v[146:149], v5 offset:22016
	s_waitcnt lgkmcnt(11)
	v_fma_f32 v10, -v182, v8, v14
	v_fma_f32 v10, -v183, v9, v10
	v_fma_f32 v10, -v54, v184, v10
	v_fma_f32 v10, -v55, v185, v10
	ds_read_b128 v[150:153], v5 offset:22032
	s_waitcnt lgkmcnt(11)
	v_fma_f32 v11, -v60, v186, v55
	v_fma_f32 v11, -v0, v187, v11
	v_fma_f32 v11, -v1, v188, v11
	v_fma_f32 v11, -v2, v189, v11
	ds_read_b128 v[178:181], v5 offset:22048
	s_waitcnt lgkmcnt(11)
	v_fma_f32 v11, -v3, v190, v11
	v_fma_f32 v11, -v191, v4, v11
	v_fma_f32 v11, -v192, v6, v11
	v_fma_f32 v11, -v193, v7, v11
	ds_read_b128 v[182:185], v5 offset:22064
	s_waitcnt lgkmcnt(11)
	v_fma_f32 v11, -v194, v8, v11
	v_fma_f32 v11, -v195, v9, v11
	v_fma_f32 v11, -v196, v10, v11
	v_fma_f32 v11, -v55, v197, v11
	ds_read_b128 v[186:189], v5 offset:22272
	s_waitcnt lgkmcnt(11)
	v_fma_f32 v12, -v60, v198, v52
	v_fma_f32 v12, -v0, v199, v12
	v_fma_f32 v12, -v1, v200, v12
	v_fma_f32 v16, -v2, v201, v12
	ds_read_b128 v[190:193], v5 offset:22288
	s_waitcnt lgkmcnt(11)
	v_fma_f32 v12, -v3, v202, v16
	v_fma_f32 v12, -v4, v203, v12
	v_fma_f32 v12, -v204, v6, v12
	v_fma_f32 v16, -v205, v7, v12
	ds_read_b128 v[194:197], v5 offset:22304
	s_waitcnt lgkmcnt(11)
	v_fma_f32 v12, -v206, v8, v16
	v_fma_f32 v12, -v207, v9, v12
	v_fma_f32 v12, -v208, v10, v12
	v_fma_f32 v12, -v209, v11, v12
	ds_read_b128 v[198:201], v5 offset:22320
	s_waitcnt lgkmcnt(11)
	v_fma_f32 v13, -v60, v214, v53
	v_fma_f32 v13, -v0, v215, v13
	v_fma_f32 v13, -v1, v216, v13
	v_fma_f32 v13, -v2, v217, v13
	ds_read_b128 v[202:205], v5 offset:22528
	s_waitcnt lgkmcnt(11)
	v_fma_f32 v13, -v3, v228, v13
	v_fma_f32 v13, -v4, v229, v13
	v_fma_f32 v13, -v6, v230, v13
	v_fma_f32 v13, -v231, v7, v13
	ds_read_b128 v[206:209], v5 offset:22544
	s_waitcnt lgkmcnt(11)
	v_fma_f32 v13, -v232, v8, v13
	v_fma_f32 v13, -v233, v9, v13
	v_fma_f32 v13, -v234, v10, v13
	v_fma_f32 v13, -v235, v11, v13
	ds_read_b128 v[214:217], v5 offset:22560
	s_waitcnt lgkmcnt(11)
	v_fma_f32 v13, -v244, v12, v13
	v_fma_f32 v13, -v53, v245, v13
	v_fma_f32 v13, -v50, v246, v13
	v_fma_f32 v13, -v51, v247, v13
	ds_read_b128 v[228:231], v5 offset:22576
	s_waitcnt lgkmcnt(11)
	v_fma_f32 v14, -v60, v146, v50
	v_fma_f32 v14, -v0, v147, v14
	v_fma_f32 v14, -v1, v148, v14
	v_fma_f32 v18, -v2, v149, v14
	ds_read_b128 v[232:235], v5 offset:22800
	s_waitcnt lgkmcnt(11)
	v_fma_f32 v14, -v3, v150, v18
	v_fma_f32 v14, -v4, v151, v14
	v_fma_f32 v14, -v6, v152, v14
	v_fma_f32 v18, -v7, v153, v14
	ds_read_b128 v[244:247], v5 offset:22784
	s_waitcnt lgkmcnt(11)
	v_fma_f32 v14, -v8, v178, v18
	v_fma_f32 v14, -v179, v9, v14
	v_fma_f32 v14, -v180, v10, v14
	v_fma_f32 v18, -v181, v11, v14
	ds_read_b128 v[146:149], v5 offset:22832
	s_waitcnt lgkmcnt(11)
	v_fma_f32 v14, -v182, v12, v18
	v_fma_f32 v14, -v183, v13, v14
	v_fma_f32 v14, -v50, v184, v14
	v_fma_f32 v14, -v51, v185, v14
	ds_read_b128 v[150:153], v5 offset:22816
	s_waitcnt lgkmcnt(11)
	v_fma_f32 v15, -v60, v186, v51
	v_fma_f32 v15, -v0, v187, v15
	v_fma_f32 v15, -v1, v188, v15
	v_fma_f32 v15, -v2, v189, v15
	ds_read_b128 v[178:181], v5 offset:23040
	s_waitcnt lgkmcnt(11)
	v_fma_f32 v15, -v3, v190, v15
	v_fma_f32 v15, -v4, v191, v15
	v_fma_f32 v15, -v6, v192, v15
	v_fma_f32 v15, -v7, v193, v15
	ds_read_b128 v[182:185], v5 offset:23056
	s_waitcnt lgkmcnt(11)
	v_fma_f32 v15, -v8, v194, v15
	v_fma_f32 v15, -v9, v195, v15
	v_fma_f32 v15, -v196, v10, v15
	v_fma_f32 v15, -v197, v11, v15
	ds_read_b128 v[186:189], v5 offset:23072
	s_waitcnt lgkmcnt(11)
	v_fma_f32 v15, -v198, v12, v15
	v_fma_f32 v15, -v199, v13, v15
	v_fma_f32 v15, -v200, v14, v15
	v_fma_f32 v15, -v51, v201, v15
	ds_read_b128 v[190:193], v5 offset:23088
	s_waitcnt lgkmcnt(11)
	v_fma_f32 v16, v60, v202, 0
	v_fma_f32 v17, v0, v203, 0
	v_fmac_f32_e32 v16, v1, v204
	v_fmac_f32_e32 v17, v2, v205
	ds_read_b128 v[194:197], v5 offset:23312
	s_waitcnt lgkmcnt(11)
	v_fmac_f32_e32 v16, v3, v206
	v_fmac_f32_e32 v17, v4, v207
	v_fmac_f32_e32 v16, v6, v208
	v_fmac_f32_e32 v17, v7, v209
	ds_read_b128 v[198:201], v5 offset:23296
	s_waitcnt lgkmcnt(11)
	v_fmac_f32_e32 v16, v8, v214
	v_fmac_f32_e32 v17, v9, v215
	v_fmac_f32_e32 v16, v10, v216
	v_fmac_f32_e32 v17, v217, v11
	ds_read_b128 v[202:205], v5 offset:23344
	s_waitcnt lgkmcnt(11)
	v_fmac_f32_e32 v16, v228, v12
	v_fmac_f32_e32 v17, v229, v13
	v_fmac_f32_e32 v16, v230, v14
	v_fmac_f32_e32 v17, v231, v15
	ds_read_b128 v[206:209], v5 offset:23328
	v_add_f32_e32 v16, v16, v17
	s_waitcnt lgkmcnt(10)
	v_fma_f32 v17, v60, v244, 0
	v_fma_f32 v22, v0, v245, 0
	v_fmac_f32_e32 v17, v1, v246
	v_fmac_f32_e32 v22, v2, v247
	ds_read_b128 v[214:217], v5 offset:23552
	v_fmac_f32_e32 v17, v3, v232
	v_fmac_f32_e32 v22, v4, v233
	v_fmac_f32_e32 v17, v6, v234
	v_fmac_f32_e32 v22, v7, v235
	ds_read_b128 v[228:231], v5 offset:23568
	s_waitcnt lgkmcnt(10)
	v_fmac_f32_e32 v17, v8, v150
	v_fmac_f32_e32 v22, v9, v151
	v_fmac_f32_e32 v17, v10, v152
	v_fmac_f32_e32 v22, v11, v153
	ds_read_b128 v[244:247], v5 offset:23584
	v_fmac_f32_e32 v17, v146, v12
	v_fmac_f32_e32 v22, v147, v13
	v_fmac_f32_e32 v17, v148, v14
	v_fmac_f32_e32 v22, v149, v15
	ds_read_b128 v[232:235], v5 offset:23600
	v_add_f32_e32 v17, v17, v22
	v_sub_f32_e32 v16, v48, v16
	v_sub_f32_e32 v17, v49, v17
	s_waitcnt lgkmcnt(11)
	v_fma_f32 v18, v60, v178, 0
	v_fma_f32 v19, v0, v179, 0
	v_fmac_f32_e32 v18, v1, v180
	v_fmac_f32_e32 v19, v2, v181
	ds_read_b128 v[150:153], v5 offset:23824
	s_waitcnt lgkmcnt(11)
	v_fmac_f32_e32 v18, v3, v182
	v_fmac_f32_e32 v19, v4, v183
	v_fmac_f32_e32 v18, v6, v184
	v_fmac_f32_e32 v19, v7, v185
	ds_read_b128 v[146:149], v5 offset:23808
	s_waitcnt lgkmcnt(11)
	v_fmac_f32_e32 v18, v8, v186
	v_fmac_f32_e32 v19, v9, v187
	v_fmac_f32_e32 v18, v10, v188
	v_fmac_f32_e32 v19, v11, v189
	ds_read_b128 v[178:181], v5 offset:23856
	s_waitcnt lgkmcnt(11)
	v_fmac_f32_e32 v18, v12, v190
	v_fmac_f32_e32 v19, v13, v191
	v_fmac_f32_e32 v18, v192, v14
	v_fmac_f32_e32 v19, v193, v15
	ds_read_b128 v[182:185], v5 offset:23840
	v_add_f32_e32 v18, v18, v19
	s_waitcnt lgkmcnt(10)
	v_fma_f32 v19, v60, v198, 0
	v_fma_f32 v24, v0, v199, 0
	v_fmac_f32_e32 v19, v1, v200
	v_fmac_f32_e32 v24, v2, v201
	ds_read_b128 v[186:189], v5 offset:24064
	v_fmac_f32_e32 v19, v3, v194
	v_fmac_f32_e32 v24, v4, v195
	v_fmac_f32_e32 v19, v6, v196
	v_fmac_f32_e32 v24, v7, v197
	ds_read_b128 v[190:193], v5 offset:24080
	s_waitcnt lgkmcnt(10)
	v_fmac_f32_e32 v19, v8, v206
	v_fmac_f32_e32 v24, v9, v207
	v_fmac_f32_e32 v19, v10, v208
	v_fmac_f32_e32 v24, v11, v209
	ds_read_b128 v[198:201], v5 offset:24096
	v_fmac_f32_e32 v19, v12, v202
	v_fmac_f32_e32 v24, v13, v203
	v_fmac_f32_e32 v19, v204, v14
	v_fmac_f32_e32 v24, v205, v15
	ds_read_b128 v[194:197], v5 offset:24112
	v_add_f32_e32 v19, v19, v24
	v_sub_f32_e32 v18, v44, v18
	v_sub_f32_e32 v19, v45, v19
	s_waitcnt lgkmcnt(11)
	v_fma_f32 v20, v60, v214, 0
	v_fma_f32 v21, v0, v215, 0
	v_fmac_f32_e32 v20, v1, v216
	v_fmac_f32_e32 v21, v2, v217
	ds_read_b128 v[206:209], v5 offset:24336
	s_waitcnt lgkmcnt(11)
	v_fmac_f32_e32 v20, v3, v228
	v_fmac_f32_e32 v21, v4, v229
	v_fmac_f32_e32 v20, v6, v230
	v_fmac_f32_e32 v21, v7, v231
	ds_read_b128 v[202:205], v5 offset:24320
	s_waitcnt lgkmcnt(11)
	v_fmac_f32_e32 v20, v8, v244
	v_fmac_f32_e32 v21, v9, v245
	v_fmac_f32_e32 v20, v10, v246
	v_fmac_f32_e32 v21, v11, v247
	ds_read_b128 v[214:217], v5 offset:24368
	s_waitcnt lgkmcnt(11)
	v_fmac_f32_e32 v20, v12, v232
	v_fmac_f32_e32 v21, v13, v233
	v_fmac_f32_e32 v20, v14, v234
	v_fmac_f32_e32 v21, v15, v235
	ds_read_b128 v[228:231], v5 offset:24352
	v_add_f32_e32 v20, v20, v21
	s_waitcnt lgkmcnt(10)
	v_fma_f32 v21, v60, v146, 0
	v_fma_f32 v26, v0, v147, 0
	v_fmac_f32_e32 v21, v1, v148
	v_fmac_f32_e32 v26, v2, v149
	ds_read_b128 v[244:247], v5 offset:24576
	v_fmac_f32_e32 v21, v3, v150
	v_fmac_f32_e32 v26, v4, v151
	v_fmac_f32_e32 v21, v6, v152
	v_fmac_f32_e32 v26, v7, v153
	ds_read_b128 v[232:235], v5 offset:24592
	s_waitcnt lgkmcnt(10)
	v_fmac_f32_e32 v21, v8, v182
	v_fmac_f32_e32 v26, v9, v183
	v_fmac_f32_e32 v21, v10, v184
	v_fmac_f32_e32 v26, v11, v185
	ds_read_b128 v[146:149], v5 offset:24608
	v_fmac_f32_e32 v21, v12, v178
	v_fmac_f32_e32 v26, v13, v179
	v_fmac_f32_e32 v21, v14, v180
	v_fmac_f32_e32 v26, v15, v181
	ds_read_b128 v[150:153], v5 offset:24624
	v_add_f32_e32 v21, v21, v26
	v_sub_f32_e32 v20, v46, v20
	v_sub_f32_e32 v21, v47, v21
	s_waitcnt lgkmcnt(11)
	v_fma_f32 v22, v60, v186, 0
	v_fma_f32 v23, v0, v187, 0
	v_fmac_f32_e32 v22, v1, v188
	v_fmac_f32_e32 v23, v2, v189
	ds_read_b128 v[182:185], v5 offset:24848
	s_waitcnt lgkmcnt(11)
	v_fmac_f32_e32 v22, v3, v190
	v_fmac_f32_e32 v23, v4, v191
	v_fmac_f32_e32 v22, v6, v192
	v_fmac_f32_e32 v23, v7, v193
	ds_read_b128 v[178:181], v5 offset:24832
	s_waitcnt lgkmcnt(11)
	v_fmac_f32_e32 v22, v8, v198
	v_fmac_f32_e32 v23, v9, v199
	v_fmac_f32_e32 v22, v10, v200
	v_fmac_f32_e32 v23, v11, v201
	ds_read_b128 v[186:189], v5 offset:24880
	s_waitcnt lgkmcnt(11)
	v_fmac_f32_e32 v22, v12, v194
	v_fmac_f32_e32 v23, v13, v195
	v_fmac_f32_e32 v22, v14, v196
	v_fmac_f32_e32 v23, v15, v197
	ds_read_b128 v[190:193], v5 offset:24864
	v_add_f32_e32 v22, v22, v23
	s_waitcnt lgkmcnt(10)
	v_fma_f32 v23, v60, v202, 0
	v_fma_f32 v28, v0, v203, 0
	v_fmac_f32_e32 v23, v1, v204
	v_fmac_f32_e32 v28, v2, v205
	ds_read_b128 v[198:201], v5 offset:25088
	v_fmac_f32_e32 v23, v3, v206
	v_fmac_f32_e32 v28, v4, v207
	v_fmac_f32_e32 v23, v6, v208
	v_fmac_f32_e32 v28, v7, v209
	ds_read_b128 v[194:197], v5 offset:25104
	s_waitcnt lgkmcnt(10)
	v_fmac_f32_e32 v23, v8, v228
	v_fmac_f32_e32 v28, v9, v229
	v_fmac_f32_e32 v23, v10, v230
	v_fmac_f32_e32 v28, v11, v231
	ds_read_b128 v[202:205], v5 offset:25120
	v_fmac_f32_e32 v23, v12, v214
	v_fmac_f32_e32 v28, v13, v215
	v_fmac_f32_e32 v23, v14, v216
	v_fmac_f32_e32 v28, v15, v217
	ds_read_b128 v[206:209], v5 offset:25136
	v_add_f32_e32 v23, v23, v28
	v_sub_f32_e32 v22, v42, v22
	v_sub_f32_e32 v23, v43, v23
	s_waitcnt lgkmcnt(11)
	v_fma_f32 v24, v60, v244, 0
	v_fma_f32 v25, v0, v245, 0
	v_fmac_f32_e32 v24, v1, v246
	v_fmac_f32_e32 v25, v2, v247
	ds_read_b128 v[228:231], v5 offset:25360
	s_waitcnt lgkmcnt(11)
	v_fmac_f32_e32 v24, v3, v232
	v_fmac_f32_e32 v25, v4, v233
	v_fmac_f32_e32 v24, v6, v234
	v_fmac_f32_e32 v25, v7, v235
	ds_read_b128 v[214:217], v5 offset:25344
	s_waitcnt lgkmcnt(11)
	v_fmac_f32_e32 v24, v8, v146
	v_fmac_f32_e32 v25, v9, v147
	v_fmac_f32_e32 v24, v10, v148
	v_fmac_f32_e32 v25, v11, v149
	ds_read_b128 v[244:247], v5 offset:25392
	s_waitcnt lgkmcnt(11)
	v_fmac_f32_e32 v24, v12, v150
	v_fmac_f32_e32 v25, v13, v151
	v_fmac_f32_e32 v24, v14, v152
	v_fmac_f32_e32 v25, v15, v153
	ds_read_b128 v[232:235], v5 offset:25376
	v_add_f32_e32 v24, v24, v25
	v_sub_f32_e32 v24, v40, v24
	s_waitcnt lgkmcnt(10)
	v_fma_f32 v25, v60, v178, 0
	v_fma_f32 v40, v0, v179, 0
	v_fmac_f32_e32 v25, v1, v180
	v_fmac_f32_e32 v40, v2, v181
	ds_read_b128 v[146:149], v5 offset:25600
	v_fmac_f32_e32 v25, v3, v182
	v_fmac_f32_e32 v40, v4, v183
	v_fmac_f32_e32 v25, v6, v184
	v_fmac_f32_e32 v40, v7, v185
	ds_read_b128 v[150:153], v5 offset:25616
	s_waitcnt lgkmcnt(10)
	v_fmac_f32_e32 v25, v8, v190
	v_fmac_f32_e32 v40, v9, v191
	v_fmac_f32_e32 v25, v10, v192
	v_fmac_f32_e32 v40, v11, v193
	ds_read_b128 v[178:181], v5 offset:25632
	v_fmac_f32_e32 v25, v12, v186
	v_fmac_f32_e32 v40, v13, v187
	v_fmac_f32_e32 v25, v14, v188
	v_fmac_f32_e32 v40, v15, v189
	ds_read_b128 v[182:185], v5 offset:25648
	v_add_f32_e32 v25, v25, v40
	v_sub_f32_e32 v25, v41, v25
	s_waitcnt lgkmcnt(11)
	v_fma_f32 v26, v60, v198, 0
	v_fma_f32 v27, v0, v199, 0
	v_fmac_f32_e32 v26, v1, v200
	v_fmac_f32_e32 v27, v2, v201
	ds_read_b128 v[190:193], v5 offset:25872
	s_waitcnt lgkmcnt(11)
	v_fmac_f32_e32 v26, v3, v194
	v_fmac_f32_e32 v27, v4, v195
	v_fmac_f32_e32 v26, v6, v196
	v_fmac_f32_e32 v27, v7, v197
	ds_read_b128 v[186:189], v5 offset:25856
	s_waitcnt lgkmcnt(11)
	v_fmac_f32_e32 v26, v8, v202
	v_fmac_f32_e32 v27, v9, v203
	v_fmac_f32_e32 v26, v10, v204
	v_fmac_f32_e32 v27, v11, v205
	ds_read_b128 v[198:201], v5 offset:25904
	s_waitcnt lgkmcnt(11)
	v_fmac_f32_e32 v26, v12, v206
	v_fmac_f32_e32 v27, v13, v207
	v_fmac_f32_e32 v26, v14, v208
	v_fmac_f32_e32 v27, v15, v209
	ds_read_b128 v[194:197], v5 offset:25888
	v_add_f32_e32 v26, v26, v27
	s_waitcnt lgkmcnt(10)
	v_fma_f32 v27, v60, v214, 0
	v_fma_f32 v28, v0, v215, 0
	v_fmac_f32_e32 v27, v1, v216
	v_fmac_f32_e32 v28, v2, v217
	ds_read_b128 v[202:205], v5 offset:26112
	v_fmac_f32_e32 v27, v3, v228
	v_fmac_f32_e32 v28, v4, v229
	v_fmac_f32_e32 v27, v6, v230
	v_fmac_f32_e32 v28, v7, v231
	ds_read_b128 v[206:209], v5 offset:26128
	s_waitcnt lgkmcnt(10)
	v_fmac_f32_e32 v27, v8, v232
	v_fmac_f32_e32 v28, v9, v233
	v_fmac_f32_e32 v27, v10, v234
	v_fmac_f32_e32 v28, v11, v235
	ds_read_b128 v[214:217], v5 offset:26144
	v_fmac_f32_e32 v27, v12, v244
	v_fmac_f32_e32 v28, v13, v245
	v_fmac_f32_e32 v27, v14, v246
	v_fmac_f32_e32 v28, v15, v247
	ds_read_b128 v[228:231], v5 offset:26160
	v_add_f32_e32 v27, v27, v28
	v_sub_f32_e32 v26, v36, v26
	v_sub_f32_e32 v27, v37, v27
	s_waitcnt lgkmcnt(11)
	v_fma_f32 v28, v60, v146, 0
	v_fma_f32 v29, v0, v147, 0
	v_fmac_f32_e32 v28, v1, v148
	v_fmac_f32_e32 v29, v2, v149
	ds_read_b128 v[232:235], v5 offset:26384
	s_waitcnt lgkmcnt(11)
	v_fmac_f32_e32 v28, v3, v150
	v_fmac_f32_e32 v29, v4, v151
	v_fmac_f32_e32 v28, v6, v152
	v_fmac_f32_e32 v29, v7, v153
	ds_read_b128 v[244:247], v5 offset:26368
	s_waitcnt lgkmcnt(11)
	v_fmac_f32_e32 v28, v8, v178
	v_fmac_f32_e32 v29, v9, v179
	v_fmac_f32_e32 v28, v10, v180
	v_fmac_f32_e32 v29, v11, v181
	ds_read_b128 v[146:149], v5 offset:26416
	s_waitcnt lgkmcnt(11)
	v_fmac_f32_e32 v28, v12, v182
	v_fmac_f32_e32 v29, v13, v183
	v_fmac_f32_e32 v28, v14, v184
	v_fmac_f32_e32 v29, v15, v185
	ds_read_b128 v[150:153], v5 offset:26400
	v_add_f32_e32 v28, v28, v29
	s_waitcnt lgkmcnt(10)
	v_fma_f32 v29, v60, v186, 0
	v_fma_f32 v36, v0, v187, 0
	v_fmac_f32_e32 v29, v1, v188
	v_fmac_f32_e32 v36, v2, v189
	ds_read_b128 v[178:181], v5 offset:26624
	v_fmac_f32_e32 v29, v3, v190
	v_fmac_f32_e32 v36, v4, v191
	v_fmac_f32_e32 v29, v6, v192
	v_fmac_f32_e32 v36, v7, v193
	ds_read_b128 v[182:185], v5 offset:26640
	s_waitcnt lgkmcnt(10)
	v_fmac_f32_e32 v29, v8, v194
	v_fmac_f32_e32 v36, v9, v195
	v_fmac_f32_e32 v29, v10, v196
	v_fmac_f32_e32 v36, v11, v197
	ds_read_b128 v[186:189], v5 offset:26656
	v_fmac_f32_e32 v29, v12, v198
	v_fmac_f32_e32 v36, v13, v199
	v_fmac_f32_e32 v29, v14, v200
	v_fmac_f32_e32 v36, v15, v201
	ds_read_b128 v[190:193], v5 offset:26672
	v_add_f32_e32 v29, v29, v36
	v_sub_f32_e32 v28, v38, v28
	v_sub_f32_e32 v29, v39, v29
	s_waitcnt lgkmcnt(11)
	v_fma_f32 v52, v60, v202, 0
	v_fma_f32 v53, v0, v203, 0
	v_fmac_f32_e32 v52, v1, v204
	v_fmac_f32_e32 v53, v2, v205
	ds_read_b128 v[194:197], v5 offset:26896
	s_waitcnt lgkmcnt(11)
	v_fmac_f32_e32 v52, v3, v206
	v_fmac_f32_e32 v53, v4, v207
	v_fmac_f32_e32 v52, v6, v208
	v_fmac_f32_e32 v53, v7, v209
	ds_read_b128 v[198:201], v5 offset:26880
	s_waitcnt lgkmcnt(11)
	v_fmac_f32_e32 v52, v8, v214
	v_fmac_f32_e32 v53, v9, v215
	v_fmac_f32_e32 v52, v10, v216
	v_fmac_f32_e32 v53, v11, v217
	ds_read_b128 v[202:205], v5 offset:26928
	s_waitcnt lgkmcnt(11)
	v_fmac_f32_e32 v52, v12, v228
	v_fmac_f32_e32 v53, v13, v229
	v_fmac_f32_e32 v52, v14, v230
	v_fmac_f32_e32 v53, v15, v231
	ds_read_b128 v[206:209], v5 offset:26912
	v_add_f32_e32 v44, v52, v53
	v_sub_f32_e32 v72, v32, v44
	s_waitcnt lgkmcnt(10)
	v_fma_f32 v32, v60, v244, 0
	v_fma_f32 v40, v0, v245, 0
	v_fmac_f32_e32 v32, v1, v246
	v_fmac_f32_e32 v40, v2, v247
	ds_read_b128 v[214:217], v5 offset:27136
	v_fmac_f32_e32 v32, v3, v232
	v_fmac_f32_e32 v40, v4, v233
	v_fmac_f32_e32 v32, v6, v234
	v_fmac_f32_e32 v40, v7, v235
	ds_read_b128 v[228:231], v5 offset:27152
	s_waitcnt lgkmcnt(10)
	v_fmac_f32_e32 v32, v8, v150
	v_fmac_f32_e32 v40, v9, v151
	v_fmac_f32_e32 v32, v10, v152
	v_fmac_f32_e32 v40, v11, v153
	ds_read_b128 v[244:247], v5 offset:27168
	v_fmac_f32_e32 v32, v12, v146
	v_fmac_f32_e32 v40, v13, v147
	v_fmac_f32_e32 v32, v14, v148
	v_fmac_f32_e32 v40, v15, v149
	ds_read_b128 v[232:235], v5 offset:27184
	v_add_f32_e32 v32, v32, v40
	v_sub_f32_e32 v32, v33, v32
	s_waitcnt lgkmcnt(11)
	v_fma_f32 v33, v60, v178, 0
	v_fma_f32 v52, v0, v179, 0
	v_fmac_f32_e32 v33, v1, v180
	v_fmac_f32_e32 v52, v2, v181
	ds_read_b128 v[150:153], v5 offset:27408
	s_waitcnt lgkmcnt(11)
	v_fmac_f32_e32 v33, v3, v182
	v_fmac_f32_e32 v52, v4, v183
	v_fmac_f32_e32 v33, v6, v184
	v_fmac_f32_e32 v52, v7, v185
	ds_read_b128 v[146:149], v5 offset:27392
	s_waitcnt lgkmcnt(11)
	v_fmac_f32_e32 v33, v8, v186
	v_fmac_f32_e32 v52, v9, v187
	v_fmac_f32_e32 v33, v10, v188
	v_fmac_f32_e32 v52, v11, v189
	ds_read_b128 v[178:181], v5 offset:27440
	s_waitcnt lgkmcnt(11)
	v_fmac_f32_e32 v33, v12, v190
	v_fmac_f32_e32 v52, v13, v191
	v_fmac_f32_e32 v33, v14, v192
	v_fmac_f32_e32 v52, v15, v193
	ds_read_b128 v[182:185], v5 offset:27424
	v_add_f32_e32 v33, v33, v52
	v_sub_f32_e32 v33, v34, v33
	s_waitcnt lgkmcnt(10)
	v_fma_f32 v34, v60, v198, 0
	v_fma_f32 v40, v0, v199, 0
	v_fmac_f32_e32 v34, v1, v200
	v_fmac_f32_e32 v40, v2, v201
	ds_read_b128 v[186:189], v5 offset:27648
	v_fmac_f32_e32 v34, v3, v194
	v_fmac_f32_e32 v40, v4, v195
	v_fmac_f32_e32 v34, v6, v196
	v_fmac_f32_e32 v40, v7, v197
	ds_read_b128 v[190:193], v5 offset:27664
	s_waitcnt lgkmcnt(10)
	v_fmac_f32_e32 v34, v8, v206
	v_fmac_f32_e32 v40, v9, v207
	v_fmac_f32_e32 v34, v10, v208
	v_fmac_f32_e32 v40, v11, v209
	ds_read_b128 v[198:201], v5 offset:27680
	v_fmac_f32_e32 v34, v12, v202
	v_fmac_f32_e32 v40, v13, v203
	v_fmac_f32_e32 v34, v14, v204
	v_fmac_f32_e32 v40, v15, v205
	ds_read_b128 v[194:197], v5 offset:27696
	v_add_f32_e32 v34, v34, v40
	v_sub_f32_e32 v34, v35, v34
	s_waitcnt lgkmcnt(11)
	v_fma_f32 v35, v60, v214, 0
	v_fma_f32 v52, v0, v215, 0
	v_fmac_f32_e32 v35, v1, v216
	v_fmac_f32_e32 v52, v2, v217
	ds_read_b128 v[206:209], v5 offset:27920
	s_waitcnt lgkmcnt(11)
	v_fmac_f32_e32 v35, v3, v228
	v_fmac_f32_e32 v52, v4, v229
	v_fmac_f32_e32 v35, v6, v230
	v_fmac_f32_e32 v52, v7, v231
	ds_read_b128 v[202:205], v5 offset:27904
	s_waitcnt lgkmcnt(11)
	v_fmac_f32_e32 v35, v8, v244
	v_fmac_f32_e32 v52, v9, v245
	v_fmac_f32_e32 v35, v10, v246
	v_fmac_f32_e32 v52, v11, v247
	ds_read_b128 v[214:217], v5 offset:27952
	s_waitcnt lgkmcnt(11)
	v_fmac_f32_e32 v35, v12, v232
	v_fmac_f32_e32 v52, v13, v233
	v_fmac_f32_e32 v35, v14, v234
	v_fmac_f32_e32 v52, v15, v235
	ds_read_b128 v[228:231], v5 offset:27936
	v_add_f32_e32 v35, v35, v52
	v_sub_f32_e32 v35, v30, v35
	s_waitcnt lgkmcnt(10)
	v_fma_f32 v30, v60, v146, 0
	v_fma_f32 v40, v0, v147, 0
	v_fmac_f32_e32 v30, v1, v148
	v_fmac_f32_e32 v40, v2, v149
	ds_read_b128 v[244:247], v5 offset:28160
	v_fmac_f32_e32 v30, v3, v150
	v_fmac_f32_e32 v40, v4, v151
	v_fmac_f32_e32 v30, v6, v152
	v_fmac_f32_e32 v40, v7, v153
	ds_read_b128 v[232:235], v5 offset:28176
	s_waitcnt lgkmcnt(10)
	v_fmac_f32_e32 v30, v8, v182
	v_fmac_f32_e32 v40, v9, v183
	v_fmac_f32_e32 v30, v10, v184
	v_fmac_f32_e32 v40, v11, v185
	ds_read_b128 v[146:149], v5 offset:28192
	v_fmac_f32_e32 v30, v12, v178
	v_fmac_f32_e32 v40, v13, v179
	v_fmac_f32_e32 v30, v14, v180
	v_fmac_f32_e32 v40, v15, v181
	ds_read_b128 v[150:153], v5 offset:28208
	v_add_f32_e32 v30, v30, v40
	v_sub_f32_e32 v36, v31, v30
	s_waitcnt lgkmcnt(11)
	v_fma_f32 v30, v60, v186, 0
	v_fma_f32 v31, v0, v187, 0
	v_fmac_f32_e32 v30, v1, v188
	v_fmac_f32_e32 v31, v2, v189
	ds_read_b128 v[182:185], v5 offset:28432
	s_waitcnt lgkmcnt(11)
	v_fmac_f32_e32 v30, v3, v190
	v_fmac_f32_e32 v31, v4, v191
	v_fmac_f32_e32 v30, v6, v192
	v_fmac_f32_e32 v31, v7, v193
	ds_read_b128 v[178:181], v5 offset:28416
	s_waitcnt lgkmcnt(11)
	v_fmac_f32_e32 v30, v8, v198
	v_fmac_f32_e32 v31, v9, v199
	v_fmac_f32_e32 v30, v10, v200
	v_fmac_f32_e32 v31, v11, v201
	ds_read_b128 v[186:189], v5 offset:28464
	s_waitcnt lgkmcnt(11)
	v_fmac_f32_e32 v30, v12, v194
	v_fmac_f32_e32 v31, v13, v195
	v_fmac_f32_e32 v30, v14, v196
	v_fmac_f32_e32 v31, v15, v197
	ds_read_b128 v[190:193], v5 offset:28448
	v_add_f32_e32 v30, v30, v31
	v_sub_f32_e32 v37, v62, v30
	s_waitcnt lgkmcnt(10)
	v_fma_f32 v30, v60, v202, 0
	v_fma_f32 v31, v0, v203, 0
	v_fmac_f32_e32 v30, v1, v204
	v_fmac_f32_e32 v31, v2, v205
	ds_read_b128 v[198:201], v5 offset:28672
	v_fmac_f32_e32 v30, v3, v206
	v_fmac_f32_e32 v31, v4, v207
	v_fmac_f32_e32 v30, v6, v208
	v_fmac_f32_e32 v31, v7, v209
	ds_read_b128 v[194:197], v5 offset:28688
	s_waitcnt lgkmcnt(10)
	v_fmac_f32_e32 v30, v8, v228
	v_fmac_f32_e32 v31, v9, v229
	v_fmac_f32_e32 v30, v10, v230
	v_fmac_f32_e32 v31, v11, v231
	ds_read_b128 v[202:205], v5 offset:28704
	v_fmac_f32_e32 v30, v12, v214
	v_fmac_f32_e32 v31, v13, v215
	v_fmac_f32_e32 v30, v14, v216
	v_fmac_f32_e32 v31, v15, v217
	ds_read_b128 v[206:209], v5 offset:28720
	v_add_f32_e32 v30, v30, v31
	v_sub_f32_e32 v38, v63, v30
	s_waitcnt lgkmcnt(11)
	v_fma_f32 v30, v60, v244, 0
	v_fma_f32 v31, v0, v245, 0
	v_fmac_f32_e32 v30, v1, v246
	v_fmac_f32_e32 v31, v2, v247
	ds_read_b128 v[228:231], v5 offset:28944
	s_waitcnt lgkmcnt(11)
	v_fmac_f32_e32 v30, v3, v232
	v_fmac_f32_e32 v31, v4, v233
	v_fmac_f32_e32 v30, v6, v234
	v_fmac_f32_e32 v31, v7, v235
	ds_read_b128 v[214:217], v5 offset:28928
	s_waitcnt lgkmcnt(11)
	v_fmac_f32_e32 v30, v8, v146
	v_fmac_f32_e32 v31, v9, v147
	v_fmac_f32_e32 v30, v10, v148
	v_fmac_f32_e32 v31, v11, v149
	ds_read_b128 v[244:247], v5 offset:28976
	s_waitcnt lgkmcnt(11)
	v_fmac_f32_e32 v30, v12, v150
	v_fmac_f32_e32 v31, v13, v151
	v_fmac_f32_e32 v30, v14, v152
	v_fmac_f32_e32 v31, v15, v153
	ds_read_b128 v[232:235], v5 offset:28960
	v_add_f32_e32 v30, v30, v31
	v_sub_f32_e32 v39, v70, v30
	s_waitcnt lgkmcnt(10)
	v_fma_f32 v30, v60, v178, 0
	v_fma_f32 v31, v0, v179, 0
	v_fmac_f32_e32 v30, v1, v180
	v_fmac_f32_e32 v31, v2, v181
	ds_read_b128 v[146:149], v5 offset:29184
	v_fmac_f32_e32 v30, v3, v182
	v_fmac_f32_e32 v31, v4, v183
	v_fmac_f32_e32 v30, v6, v184
	v_fmac_f32_e32 v31, v7, v185
	ds_read_b128 v[150:153], v5 offset:29200
	s_waitcnt lgkmcnt(10)
	v_fmac_f32_e32 v30, v8, v190
	v_fmac_f32_e32 v31, v9, v191
	v_fmac_f32_e32 v30, v10, v192
	v_fmac_f32_e32 v31, v11, v193
	ds_read_b128 v[178:181], v5 offset:29216
	v_fmac_f32_e32 v30, v12, v186
	v_fmac_f32_e32 v31, v13, v187
	v_fmac_f32_e32 v30, v14, v188
	v_fmac_f32_e32 v31, v15, v189
	ds_read_b128 v[182:185], v5 offset:29232
	v_add_f32_e32 v30, v30, v31
	v_sub_f32_e32 v40, v71, v30
	s_waitcnt lgkmcnt(11)
	v_fma_f32 v30, v60, v198, 0
	v_fma_f32 v31, v0, v199, 0
	v_fmac_f32_e32 v30, v1, v200
	v_fmac_f32_e32 v31, v2, v201
	ds_read_b128 v[190:193], v5 offset:29456
	s_waitcnt lgkmcnt(11)
	v_fmac_f32_e32 v30, v3, v194
	v_fmac_f32_e32 v31, v4, v195
	v_fmac_f32_e32 v30, v6, v196
	v_fmac_f32_e32 v31, v7, v197
	ds_read_b128 v[186:189], v5 offset:29440
	s_waitcnt lgkmcnt(11)
	v_fmac_f32_e32 v30, v8, v202
	v_fmac_f32_e32 v31, v9, v203
	v_fmac_f32_e32 v30, v10, v204
	v_fmac_f32_e32 v31, v11, v205
	ds_read_b128 v[198:201], v5 offset:29488
	s_waitcnt lgkmcnt(11)
	v_fmac_f32_e32 v30, v12, v206
	v_fmac_f32_e32 v31, v13, v207
	v_fmac_f32_e32 v30, v14, v208
	v_fmac_f32_e32 v31, v15, v209
	ds_read_b128 v[194:197], v5 offset:29472
	v_add_f32_e32 v30, v30, v31
	v_sub_f32_e32 v41, v58, v30
	s_waitcnt lgkmcnt(10)
	v_fma_f32 v30, v60, v214, 0
	v_fma_f32 v31, v0, v215, 0
	v_fmac_f32_e32 v30, v1, v216
	v_fmac_f32_e32 v31, v2, v217
	ds_read_b128 v[202:205], v5 offset:29696
	v_fmac_f32_e32 v30, v3, v228
	v_fmac_f32_e32 v31, v4, v229
	v_fmac_f32_e32 v30, v6, v230
	v_fmac_f32_e32 v31, v7, v231
	ds_read_b128 v[206:209], v5 offset:29712
	s_waitcnt lgkmcnt(10)
	v_fmac_f32_e32 v30, v8, v232
	v_fmac_f32_e32 v31, v9, v233
	v_fmac_f32_e32 v30, v10, v234
	v_fmac_f32_e32 v31, v11, v235
	ds_read_b128 v[214:217], v5 offset:29728
	v_fmac_f32_e32 v30, v12, v244
	v_fmac_f32_e32 v31, v13, v245
	v_fmac_f32_e32 v30, v14, v246
	v_fmac_f32_e32 v31, v15, v247
	ds_read_b128 v[228:231], v5 offset:29744
	v_add_f32_e32 v30, v30, v31
	v_sub_f32_e32 v42, v59, v30
	s_waitcnt lgkmcnt(11)
	v_fma_f32 v30, v60, v146, 0
	v_fma_f32 v31, v0, v147, 0
	v_fmac_f32_e32 v30, v1, v148
	v_fmac_f32_e32 v31, v2, v149
	ds_read_b128 v[232:235], v5 offset:29968
	s_waitcnt lgkmcnt(11)
	v_fmac_f32_e32 v30, v3, v150
	v_fmac_f32_e32 v31, v4, v151
	v_fmac_f32_e32 v30, v6, v152
	v_fmac_f32_e32 v31, v7, v153
	ds_read_b128 v[244:247], v5 offset:29952
	s_waitcnt lgkmcnt(11)
	v_fmac_f32_e32 v30, v8, v178
	v_fmac_f32_e32 v31, v9, v179
	v_fmac_f32_e32 v30, v10, v180
	v_fmac_f32_e32 v31, v11, v181
	ds_read_b128 v[146:149], v5 offset:30000
	s_waitcnt lgkmcnt(11)
	v_fmac_f32_e32 v30, v12, v182
	v_fmac_f32_e32 v31, v13, v183
	v_fmac_f32_e32 v30, v14, v184
	v_fmac_f32_e32 v31, v15, v185
	ds_read_b128 v[150:153], v5 offset:29984
	v_add_f32_e32 v30, v30, v31
	v_sub_f32_e32 v43, v56, v30
	s_waitcnt lgkmcnt(10)
	v_fma_f32 v30, v60, v186, 0
	v_fma_f32 v31, v0, v187, 0
	v_fmac_f32_e32 v30, v1, v188
	v_fmac_f32_e32 v31, v2, v189
	ds_read_b128 v[178:181], v5 offset:30208
	v_fmac_f32_e32 v30, v3, v190
	v_fmac_f32_e32 v31, v4, v191
	v_fmac_f32_e32 v30, v6, v192
	v_fmac_f32_e32 v31, v7, v193
	ds_read_b128 v[182:185], v5 offset:30224
	s_waitcnt lgkmcnt(10)
	v_fmac_f32_e32 v30, v8, v194
	v_fmac_f32_e32 v31, v9, v195
	v_fmac_f32_e32 v30, v10, v196
	v_fmac_f32_e32 v31, v11, v197
	ds_read_b128 v[186:189], v5 offset:30240
	v_fmac_f32_e32 v30, v12, v198
	v_fmac_f32_e32 v31, v13, v199
	v_fmac_f32_e32 v30, v14, v200
	v_fmac_f32_e32 v31, v15, v201
	ds_read_b128 v[190:193], v5 offset:30256
	v_add_f32_e32 v30, v30, v31
	v_sub_f32_e32 v44, v57, v30
	s_waitcnt lgkmcnt(11)
	v_fma_f32 v30, v60, v202, 0
	v_fma_f32 v31, v0, v203, 0
	v_fmac_f32_e32 v30, v1, v204
	v_fmac_f32_e32 v31, v2, v205
	ds_read_b128 v[194:197], v5 offset:30480
	s_waitcnt lgkmcnt(11)
	v_fmac_f32_e32 v30, v3, v206
	v_fmac_f32_e32 v31, v4, v207
	v_fmac_f32_e32 v30, v6, v208
	v_fmac_f32_e32 v31, v7, v209
	ds_read_b128 v[198:201], v5 offset:30464
	s_waitcnt lgkmcnt(11)
	v_fmac_f32_e32 v30, v8, v214
	v_fmac_f32_e32 v31, v9, v215
	v_fmac_f32_e32 v30, v10, v216
	v_fmac_f32_e32 v31, v11, v217
	ds_read_b128 v[202:205], v5 offset:30512
	s_waitcnt lgkmcnt(11)
	v_fmac_f32_e32 v30, v12, v228
	v_fmac_f32_e32 v31, v13, v229
	v_fmac_f32_e32 v30, v14, v230
	v_fmac_f32_e32 v31, v15, v231
	ds_read_b128 v[206:209], v5 offset:30496
	v_add_f32_e32 v30, v30, v31
	v_sub_f32_e32 v45, v84, v30
	s_waitcnt lgkmcnt(10)
	v_fma_f32 v30, v60, v244, 0
	v_fma_f32 v31, v0, v245, 0
	v_fmac_f32_e32 v30, v1, v246
	v_fmac_f32_e32 v31, v2, v247
	ds_read_b128 v[214:217], v5 offset:30720
	v_fmac_f32_e32 v30, v3, v232
	v_fmac_f32_e32 v31, v4, v233
	v_fmac_f32_e32 v30, v6, v234
	v_fmac_f32_e32 v31, v7, v235
	ds_read_b128 v[228:231], v5 offset:30736
	s_waitcnt lgkmcnt(10)
	v_fmac_f32_e32 v30, v8, v150
	v_fmac_f32_e32 v31, v9, v151
	v_fmac_f32_e32 v30, v10, v152
	v_fmac_f32_e32 v31, v11, v153
	ds_read_b128 v[244:247], v5 offset:30752
	v_fmac_f32_e32 v30, v12, v146
	v_fmac_f32_e32 v31, v13, v147
	v_fmac_f32_e32 v30, v14, v148
	v_fmac_f32_e32 v31, v15, v149
	ds_read_b128 v[232:235], v5 offset:30768
	v_add_f32_e32 v30, v30, v31
	v_sub_f32_e32 v46, v85, v30
	s_waitcnt lgkmcnt(11)
	v_fma_f32 v30, v60, v178, 0
	v_fma_f32 v31, v0, v179, 0
	v_fmac_f32_e32 v30, v1, v180
	v_fmac_f32_e32 v31, v2, v181
	ds_read_b128 v[150:153], v5 offset:30992
	s_waitcnt lgkmcnt(11)
	v_fmac_f32_e32 v30, v3, v182
	v_fmac_f32_e32 v31, v4, v183
	v_fmac_f32_e32 v30, v6, v184
	v_fmac_f32_e32 v31, v7, v185
	ds_read_b128 v[146:149], v5 offset:30976
	s_waitcnt lgkmcnt(11)
	v_fmac_f32_e32 v30, v8, v186
	v_fmac_f32_e32 v31, v9, v187
	v_fmac_f32_e32 v30, v10, v188
	v_fmac_f32_e32 v31, v11, v189
	ds_read_b128 v[178:181], v5 offset:31024
	s_waitcnt lgkmcnt(11)
	v_fmac_f32_e32 v30, v12, v190
	v_fmac_f32_e32 v31, v13, v191
	v_fmac_f32_e32 v30, v14, v192
	v_fmac_f32_e32 v31, v15, v193
	ds_read_b128 v[182:185], v5 offset:31008
	v_add_f32_e32 v30, v30, v31
	v_sub_f32_e32 v47, v78, v30
	s_waitcnt lgkmcnt(10)
	v_fma_f32 v30, v60, v198, 0
	v_fma_f32 v31, v0, v199, 0
	v_fmac_f32_e32 v30, v1, v200
	v_fmac_f32_e32 v31, v2, v201
	ds_read_b128 v[186:189], v5 offset:31232
	v_fmac_f32_e32 v30, v3, v194
	v_fmac_f32_e32 v31, v4, v195
	v_fmac_f32_e32 v30, v6, v196
	v_fmac_f32_e32 v31, v7, v197
	ds_read_b128 v[190:193], v5 offset:31248
	s_waitcnt lgkmcnt(10)
	v_fmac_f32_e32 v30, v8, v206
	v_fmac_f32_e32 v31, v9, v207
	v_fmac_f32_e32 v30, v10, v208
	v_fmac_f32_e32 v31, v11, v209
	ds_read_b128 v[198:201], v5 offset:31264
	v_fmac_f32_e32 v30, v12, v202
	v_fmac_f32_e32 v31, v13, v203
	v_fmac_f32_e32 v30, v14, v204
	v_fmac_f32_e32 v31, v15, v205
	ds_read_b128 v[194:197], v5 offset:31280
	v_add_f32_e32 v30, v30, v31
	v_sub_f32_e32 v48, v79, v30
	s_waitcnt lgkmcnt(11)
	v_fma_f32 v30, v60, v214, 0
	v_fma_f32 v31, v0, v215, 0
	v_fmac_f32_e32 v30, v1, v216
	v_fmac_f32_e32 v31, v2, v217
	ds_read_b128 v[206:209], v5 offset:31504
	s_waitcnt lgkmcnt(11)
	v_fmac_f32_e32 v30, v3, v228
	v_fmac_f32_e32 v31, v4, v229
	v_fmac_f32_e32 v30, v6, v230
	v_fmac_f32_e32 v31, v7, v231
	ds_read_b128 v[202:205], v5 offset:31488
	s_waitcnt lgkmcnt(11)
	v_fmac_f32_e32 v30, v8, v244
	v_fmac_f32_e32 v31, v9, v245
	v_fmac_f32_e32 v30, v10, v246
	v_fmac_f32_e32 v31, v11, v247
	ds_read_b128 v[214:217], v5 offset:31536
	s_waitcnt lgkmcnt(11)
	v_fmac_f32_e32 v30, v12, v232
	v_fmac_f32_e32 v31, v13, v233
	v_fmac_f32_e32 v30, v14, v234
	v_fmac_f32_e32 v31, v15, v235
	ds_read_b128 v[228:231], v5 offset:31520
	v_add_f32_e32 v30, v30, v31
	v_sub_f32_e32 v49, v76, v30
	s_waitcnt lgkmcnt(10)
	v_fma_f32 v30, v60, v146, 0
	v_fma_f32 v31, v0, v147, 0
	v_fmac_f32_e32 v30, v1, v148
	v_fmac_f32_e32 v31, v2, v149
	ds_read_b128 v[244:247], v5 offset:31744
	v_fmac_f32_e32 v30, v3, v150
	v_fmac_f32_e32 v31, v4, v151
	v_fmac_f32_e32 v30, v6, v152
	v_fmac_f32_e32 v31, v7, v153
	ds_read_b128 v[232:235], v5 offset:31760
	s_waitcnt lgkmcnt(10)
	v_fmac_f32_e32 v30, v8, v182
	v_fmac_f32_e32 v31, v9, v183
	v_fmac_f32_e32 v30, v10, v184
	v_fmac_f32_e32 v31, v11, v185
	ds_read_b128 v[146:149], v5 offset:31776
	v_fmac_f32_e32 v30, v12, v178
	v_fmac_f32_e32 v31, v13, v179
	v_fmac_f32_e32 v30, v14, v180
	v_fmac_f32_e32 v31, v15, v181
	ds_read_b128 v[150:153], v5 offset:31792
	v_add_f32_e32 v30, v30, v31
	v_sub_f32_e32 v50, v77, v30
	s_waitcnt lgkmcnt(11)
	v_fma_f32 v30, v60, v186, 0
	v_fma_f32 v31, v0, v187, 0
	v_fmac_f32_e32 v30, v1, v188
	v_fmac_f32_e32 v31, v2, v189
	ds_read_b128 v[182:185], v5 offset:32016
	s_waitcnt lgkmcnt(11)
	v_fmac_f32_e32 v30, v3, v190
	v_fmac_f32_e32 v31, v4, v191
	v_fmac_f32_e32 v30, v6, v192
	v_fmac_f32_e32 v31, v7, v193
	ds_read_b128 v[178:181], v5 offset:32000
	s_waitcnt lgkmcnt(11)
	v_fmac_f32_e32 v30, v8, v198
	v_fmac_f32_e32 v31, v9, v199
	v_fmac_f32_e32 v30, v10, v200
	v_fmac_f32_e32 v31, v11, v201
	ds_read_b128 v[186:189], v5 offset:32048
	s_waitcnt lgkmcnt(11)
	v_fmac_f32_e32 v30, v12, v194
	v_fmac_f32_e32 v31, v13, v195
	v_fmac_f32_e32 v30, v14, v196
	v_fmac_f32_e32 v31, v15, v197
	ds_read_b128 v[190:193], v5 offset:32032
	v_add_f32_e32 v30, v30, v31
	v_sub_f32_e32 v51, v74, v30
	s_waitcnt lgkmcnt(10)
	v_fma_f32 v30, v60, v202, 0
	v_fma_f32 v31, v0, v203, 0
	v_fmac_f32_e32 v30, v1, v204
	v_fmac_f32_e32 v31, v2, v205
	ds_read_b128 v[198:201], v5 offset:32256
	v_fmac_f32_e32 v30, v3, v206
	v_fmac_f32_e32 v31, v4, v207
	v_fmac_f32_e32 v30, v6, v208
	v_fmac_f32_e32 v31, v7, v209
	ds_read_b128 v[194:197], v5 offset:32272
	s_waitcnt lgkmcnt(10)
	v_fmac_f32_e32 v30, v8, v228
	v_fmac_f32_e32 v31, v9, v229
	v_fmac_f32_e32 v30, v10, v230
	v_fmac_f32_e32 v31, v11, v231
	ds_read_b128 v[202:205], v5 offset:32288
	v_fmac_f32_e32 v30, v12, v214
	v_fmac_f32_e32 v31, v13, v215
	v_fmac_f32_e32 v30, v14, v216
	v_fmac_f32_e32 v31, v15, v217
	ds_read_b128 v[206:209], v5 offset:32304
	v_add_f32_e32 v30, v30, v31
	v_sub_f32_e32 v52, v75, v30
	s_waitcnt lgkmcnt(11)
	v_fma_f32 v30, v60, v244, 0
	v_fma_f32 v31, v0, v245, 0
	v_fmac_f32_e32 v30, v1, v246
	v_fmac_f32_e32 v31, v2, v247
	ds_read_b128 v[228:231], v5 offset:32528
	s_waitcnt lgkmcnt(11)
	v_fmac_f32_e32 v30, v3, v232
	v_fmac_f32_e32 v31, v4, v233
	v_fmac_f32_e32 v30, v6, v234
	v_fmac_f32_e32 v31, v7, v235
	ds_read_b128 v[214:217], v5 offset:32512
	s_waitcnt lgkmcnt(11)
	v_fmac_f32_e32 v30, v8, v146
	v_fmac_f32_e32 v31, v9, v147
	v_fmac_f32_e32 v30, v10, v148
	v_fmac_f32_e32 v31, v11, v149
	ds_read_b128 v[244:247], v5 offset:32560
	s_waitcnt lgkmcnt(11)
	v_fmac_f32_e32 v30, v12, v150
	v_fmac_f32_e32 v31, v13, v151
	v_fmac_f32_e32 v30, v14, v152
	v_fmac_f32_e32 v31, v15, v153
	ds_read_b128 v[232:235], v5 offset:32544
	v_add_f32_e32 v30, v30, v31
	v_sub_f32_e32 v53, v92, v30
	s_waitcnt lgkmcnt(10)
	v_fma_f32 v30, v60, v178, 0
	v_fma_f32 v31, v0, v179, 0
	v_fmac_f32_e32 v30, v1, v180
	v_fmac_f32_e32 v31, v2, v181
	ds_read_b128 v[146:149], v5 offset:32768
	v_fmac_f32_e32 v30, v3, v182
	v_fmac_f32_e32 v31, v4, v183
	v_fmac_f32_e32 v30, v6, v184
	v_fmac_f32_e32 v31, v7, v185
	ds_read_b128 v[150:153], v5 offset:32784
	s_waitcnt lgkmcnt(10)
	v_fmac_f32_e32 v30, v8, v190
	v_fmac_f32_e32 v31, v9, v191
	v_fmac_f32_e32 v30, v10, v192
	v_fmac_f32_e32 v31, v11, v193
	ds_read_b128 v[178:181], v5 offset:32800
	v_fmac_f32_e32 v30, v12, v186
	v_fmac_f32_e32 v31, v13, v187
	v_fmac_f32_e32 v30, v14, v188
	v_fmac_f32_e32 v31, v15, v189
	ds_read_b128 v[182:185], v5 offset:32816
	v_add_f32_e32 v30, v30, v31
	v_sub_f32_e32 v54, v93, v30
	s_waitcnt lgkmcnt(11)
	v_fma_f32 v30, v60, v198, 0
	v_fma_f32 v31, v0, v199, 0
	v_fmac_f32_e32 v30, v1, v200
	v_fmac_f32_e32 v31, v2, v201
	ds_read_b128 v[190:193], v5 offset:33040
	s_waitcnt lgkmcnt(11)
	v_fmac_f32_e32 v30, v3, v194
	v_fmac_f32_e32 v31, v4, v195
	v_fmac_f32_e32 v30, v6, v196
	v_fmac_f32_e32 v31, v7, v197
	ds_read_b128 v[186:189], v5 offset:33024
	s_waitcnt lgkmcnt(11)
	v_fmac_f32_e32 v30, v8, v202
	v_fmac_f32_e32 v31, v9, v203
	v_fmac_f32_e32 v30, v10, v204
	v_fmac_f32_e32 v31, v11, v205
	ds_read_b128 v[198:201], v5 offset:33072
	s_waitcnt lgkmcnt(11)
	v_fmac_f32_e32 v30, v12, v206
	v_fmac_f32_e32 v31, v13, v207
	v_fmac_f32_e32 v30, v14, v208
	v_fmac_f32_e32 v31, v15, v209
	ds_read_b128 v[194:197], v5 offset:33056
	v_add_f32_e32 v30, v30, v31
	v_sub_f32_e32 v55, v88, v30
	s_waitcnt lgkmcnt(10)
	v_fma_f32 v30, v60, v214, 0
	v_fma_f32 v31, v0, v215, 0
	v_fmac_f32_e32 v30, v1, v216
	v_fmac_f32_e32 v31, v2, v217
	ds_read_b128 v[202:205], v5 offset:33280
	v_fmac_f32_e32 v30, v3, v228
	v_fmac_f32_e32 v31, v4, v229
	v_fmac_f32_e32 v30, v6, v230
	v_fmac_f32_e32 v31, v7, v231
	ds_read_b128 v[206:209], v5 offset:33296
	s_waitcnt lgkmcnt(10)
	v_fmac_f32_e32 v30, v8, v232
	v_fmac_f32_e32 v31, v9, v233
	v_fmac_f32_e32 v30, v10, v234
	v_fmac_f32_e32 v31, v11, v235
	ds_read_b128 v[214:217], v5 offset:33312
	v_fmac_f32_e32 v30, v12, v244
	v_fmac_f32_e32 v31, v13, v245
	v_fmac_f32_e32 v30, v14, v246
	v_fmac_f32_e32 v31, v15, v247
	ds_read_b128 v[228:231], v5 offset:33328
	v_add_f32_e32 v30, v30, v31
	v_sub_f32_e32 v56, v89, v30
	s_waitcnt lgkmcnt(11)
	v_fma_f32 v30, v60, v146, 0
	v_fma_f32 v31, v0, v147, 0
	v_fmac_f32_e32 v30, v1, v148
	v_fmac_f32_e32 v31, v2, v149
	ds_read_b128 v[232:235], v5 offset:33552
	s_waitcnt lgkmcnt(11)
	v_fmac_f32_e32 v30, v3, v150
	v_fmac_f32_e32 v31, v4, v151
	v_fmac_f32_e32 v30, v6, v152
	v_fmac_f32_e32 v31, v7, v153
	ds_read_b128 v[244:247], v5 offset:33536
	s_waitcnt lgkmcnt(11)
	v_fmac_f32_e32 v30, v8, v178
	v_fmac_f32_e32 v31, v9, v179
	v_fmac_f32_e32 v30, v10, v180
	v_fmac_f32_e32 v31, v11, v181
	ds_read_b128 v[146:149], v5 offset:33584
	s_waitcnt lgkmcnt(11)
	v_fmac_f32_e32 v30, v12, v182
	v_fmac_f32_e32 v31, v13, v183
	v_fmac_f32_e32 v30, v14, v184
	v_fmac_f32_e32 v31, v15, v185
	ds_read_b128 v[150:153], v5 offset:33568
	v_add_f32_e32 v30, v30, v31
	v_sub_f32_e32 v57, v94, v30
	s_waitcnt lgkmcnt(10)
	v_fma_f32 v30, v60, v186, 0
	v_fma_f32 v31, v0, v187, 0
	v_fmac_f32_e32 v30, v1, v188
	v_fmac_f32_e32 v31, v2, v189
	ds_read_b128 v[178:181], v5 offset:33792
	v_fmac_f32_e32 v30, v3, v190
	v_fmac_f32_e32 v31, v4, v191
	v_fmac_f32_e32 v30, v6, v192
	v_fmac_f32_e32 v31, v7, v193
	ds_read_b128 v[182:185], v5 offset:33808
	s_waitcnt lgkmcnt(10)
	v_fmac_f32_e32 v30, v8, v194
	v_fmac_f32_e32 v31, v9, v195
	v_fmac_f32_e32 v30, v10, v196
	v_fmac_f32_e32 v31, v11, v197
	ds_read_b128 v[186:189], v5 offset:33824
	v_fmac_f32_e32 v30, v12, v198
	v_fmac_f32_e32 v31, v13, v199
	v_fmac_f32_e32 v30, v14, v200
	v_fmac_f32_e32 v31, v15, v201
	ds_read_b128 v[190:193], v5 offset:33840
	v_add_f32_e32 v30, v30, v31
	v_sub_f32_e32 v58, v95, v30
	s_waitcnt lgkmcnt(11)
	v_fma_f32 v30, v60, v202, 0
	v_fma_f32 v31, v0, v203, 0
	v_fmac_f32_e32 v30, v1, v204
	v_fmac_f32_e32 v31, v2, v205
	ds_read_b128 v[194:197], v5 offset:34064
	s_waitcnt lgkmcnt(11)
	v_fmac_f32_e32 v30, v3, v206
	v_fmac_f32_e32 v31, v4, v207
	v_fmac_f32_e32 v30, v6, v208
	v_fmac_f32_e32 v31, v7, v209
	ds_read_b128 v[198:201], v5 offset:34048
	s_waitcnt lgkmcnt(11)
	v_fmac_f32_e32 v30, v8, v214
	v_fmac_f32_e32 v31, v9, v215
	v_fmac_f32_e32 v30, v10, v216
	v_fmac_f32_e32 v31, v11, v217
	ds_read_b128 v[202:205], v5 offset:34096
	s_waitcnt lgkmcnt(11)
	v_fmac_f32_e32 v30, v12, v228
	v_fmac_f32_e32 v31, v13, v229
	v_fmac_f32_e32 v30, v14, v230
	v_fmac_f32_e32 v31, v15, v231
	ds_read_b128 v[206:209], v5 offset:34080
	v_add_f32_e32 v30, v30, v31
	v_sub_f32_e32 v59, v90, v30
	s_waitcnt lgkmcnt(10)
	v_fma_f32 v30, v60, v244, 0
	v_fma_f32 v31, v0, v245, 0
	v_fmac_f32_e32 v30, v1, v246
	v_fmac_f32_e32 v31, v2, v247
	ds_read_b128 v[214:217], v5 offset:34304
	v_fmac_f32_e32 v30, v3, v232
	v_fmac_f32_e32 v31, v4, v233
	v_fmac_f32_e32 v30, v6, v234
	v_fmac_f32_e32 v31, v7, v235
	ds_read_b128 v[228:231], v5 offset:34320
	s_waitcnt lgkmcnt(10)
	v_fmac_f32_e32 v30, v8, v150
	v_fmac_f32_e32 v31, v9, v151
	v_fmac_f32_e32 v30, v10, v152
	v_fmac_f32_e32 v31, v11, v153
	ds_read_b128 v[244:247], v5 offset:34336
	v_fmac_f32_e32 v30, v12, v146
	v_fmac_f32_e32 v31, v13, v147
	v_fmac_f32_e32 v30, v14, v148
	v_fmac_f32_e32 v31, v15, v149
	ds_read_b128 v[232:235], v5 offset:34352
	v_add_f32_e32 v30, v30, v31
	v_sub_f32_e32 v61, v91, v30
	s_waitcnt lgkmcnt(11)
	v_fma_f32 v30, v60, v178, 0
	v_fma_f32 v31, v0, v179, 0
	v_fmac_f32_e32 v30, v1, v180
	v_fmac_f32_e32 v31, v2, v181
	ds_read_b128 v[150:153], v5 offset:34576
	s_waitcnt lgkmcnt(11)
	v_fmac_f32_e32 v30, v3, v182
	v_fmac_f32_e32 v31, v4, v183
	v_fmac_f32_e32 v30, v6, v184
	v_fmac_f32_e32 v31, v7, v185
	ds_read_b128 v[146:149], v5 offset:34560
	s_waitcnt lgkmcnt(11)
	v_fmac_f32_e32 v30, v8, v186
	v_fmac_f32_e32 v31, v9, v187
	v_fmac_f32_e32 v30, v10, v188
	v_fmac_f32_e32 v31, v11, v189
	ds_read_b128 v[178:181], v5 offset:34608
	s_waitcnt lgkmcnt(11)
	v_fmac_f32_e32 v30, v12, v190
	v_fmac_f32_e32 v31, v13, v191
	v_fmac_f32_e32 v30, v14, v192
	v_fmac_f32_e32 v31, v15, v193
	ds_read_b128 v[182:185], v5 offset:34592
	v_add_f32_e32 v30, v30, v31
	v_sub_f32_e32 v62, v96, v30
	s_waitcnt lgkmcnt(10)
	v_fma_f32 v30, v60, v198, 0
	v_fma_f32 v31, v0, v199, 0
	v_fmac_f32_e32 v30, v1, v200
	v_fmac_f32_e32 v31, v2, v201
	ds_read_b128 v[186:189], v5 offset:22848
	v_fmac_f32_e32 v30, v3, v194
	v_fmac_f32_e32 v31, v4, v195
	v_fmac_f32_e32 v30, v6, v196
	v_fmac_f32_e32 v31, v7, v197
	ds_read_b128 v[190:193], v5 offset:23104
	s_waitcnt lgkmcnt(10)
	v_fmac_f32_e32 v30, v8, v206
	v_fmac_f32_e32 v31, v9, v207
	v_fmac_f32_e32 v30, v10, v208
	v_fmac_f32_e32 v31, v11, v209
	ds_read_b128 v[198:201], v5 offset:23360
	v_fmac_f32_e32 v30, v12, v202
	v_fmac_f32_e32 v31, v13, v203
	v_fmac_f32_e32 v30, v14, v204
	v_fmac_f32_e32 v31, v15, v205
	ds_read_b128 v[194:197], v5 offset:23616
	v_add_f32_e32 v30, v30, v31
	v_sub_f32_e32 v63, v97, v30
	s_waitcnt lgkmcnt(11)
	v_fma_f32 v30, v60, v214, 0
	v_fma_f32 v31, v0, v215, 0
	v_fmac_f32_e32 v30, v1, v216
	v_fmac_f32_e32 v31, v2, v217
	ds_read_b128 v[206:209], v5 offset:23872
	s_waitcnt lgkmcnt(11)
	v_fmac_f32_e32 v30, v3, v228
	v_fmac_f32_e32 v31, v4, v229
	v_fmac_f32_e32 v30, v6, v230
	v_fmac_f32_e32 v31, v7, v231
	ds_read_b128 v[202:205], v5 offset:23888
	s_waitcnt lgkmcnt(11)
	v_fmac_f32_e32 v30, v8, v244
	v_fmac_f32_e32 v31, v9, v245
	v_fmac_f32_e32 v30, v10, v246
	v_fmac_f32_e32 v31, v11, v247
	ds_read_b128 v[214:217], v5 offset:24128
	s_waitcnt lgkmcnt(11)
	v_fmac_f32_e32 v30, v12, v232
	v_fmac_f32_e32 v31, v13, v233
	v_fmac_f32_e32 v30, v14, v234
	v_fmac_f32_e32 v31, v15, v235
	ds_read_b128 v[228:231], v5 offset:24144
	v_add_f32_e32 v30, v30, v31
	v_sub_f32_e32 v70, v98, v30
	s_waitcnt lgkmcnt(10)
	v_fma_f32 v30, v60, v146, 0
	v_fma_f32 v31, v0, v147, 0
	v_fmac_f32_e32 v30, v1, v148
	v_fmac_f32_e32 v31, v2, v149
	ds_read_b128 v[244:247], v5 offset:24384
	v_fmac_f32_e32 v30, v3, v150
	v_fmac_f32_e32 v31, v4, v151
	v_fmac_f32_e32 v30, v6, v152
	v_fmac_f32_e32 v31, v7, v153
	ds_read_b128 v[232:235], v5 offset:24400
	s_waitcnt lgkmcnt(10)
	v_fmac_f32_e32 v30, v8, v182
	v_fmac_f32_e32 v31, v9, v183
	v_fmac_f32_e32 v30, v10, v184
	v_fmac_f32_e32 v31, v11, v185
	ds_read_b128 v[146:149], v5 offset:24640
	v_fmac_f32_e32 v30, v12, v178
	v_fmac_f32_e32 v31, v13, v179
	v_fmac_f32_e32 v30, v14, v180
	v_fmac_f32_e32 v31, v15, v181
	ds_read_b128 v[150:153], v5 offset:24656
	v_add_f32_e32 v30, v30, v31
	v_sub_f32_e32 v71, v99, v30
	s_waitcnt lgkmcnt(11)
	v_fma_f32 v30, -v16, v186, v17
	v_fma_f32 v17, -v17, v187, v30
	v_fma_f32 v17, -v18, v188, v17
	v_fma_f32 v17, -v19, v189, v17
	ds_read_b128 v[182:185], v5 offset:24896
	s_waitcnt lgkmcnt(11)
	v_fma_f32 v30, -v16, v190, v18
	v_fma_f32 v30, -v191, v17, v30
	v_fma_f32 v18, -v18, v192, v30
	v_fma_f32 v18, -v19, v193, v18
	ds_read_b128 v[178:181], v5 offset:24912
	s_waitcnt lgkmcnt(11)
	v_fma_f32 v30, -v16, v198, v19
	v_fma_f32 v30, -v199, v17, v30
	v_fma_f32 v30, -v200, v18, v30
	v_fma_f32 v19, -v19, v201, v30
	ds_read_b128 v[186:189], v5 offset:24928
	s_waitcnt lgkmcnt(11)
	v_fma_f32 v20, -v16, v194, v20
	v_fma_f32 v20, -v195, v17, v20
	v_fma_f32 v20, -v196, v18, v20
	v_fma_f32 v20, -v197, v19, v20
	ds_read_b128 v[190:193], v5 offset:25152
	s_waitcnt lgkmcnt(11)
	v_fma_f32 v30, -v16, v206, v21
	v_fma_f32 v30, -v207, v17, v30
	v_fma_f32 v30, -v208, v18, v30
	v_fma_f32 v30, -v209, v19, v30
	ds_read_b128 v[198:201], v5 offset:25168
	s_waitcnt lgkmcnt(11)
	v_fma_f32 v30, -v202, v20, v30
	v_fma_f32 v21, -v21, v203, v30
	v_fma_f32 v21, -v22, v204, v21
	v_fma_f32 v21, -v23, v205, v21
	ds_read_b128 v[194:197], v5 offset:25184
	s_waitcnt lgkmcnt(11)
	v_fma_f32 v30, -v16, v214, v22
	v_fma_f32 v30, -v17, v215, v30
	v_fma_f32 v30, -v216, v18, v30
	v_fma_f32 v30, -v217, v19, v30
	ds_read_b128 v[206:209], v5 offset:25408
	s_waitcnt lgkmcnt(11)
	v_fma_f32 v30, -v228, v20, v30
	v_fma_f32 v30, -v229, v21, v30
	v_fma_f32 v22, -v22, v230, v30
	v_fma_f32 v22, -v23, v231, v22
	ds_read_b128 v[202:205], v5 offset:25424
	s_waitcnt lgkmcnt(11)
	v_fma_f32 v30, -v16, v244, v23
	v_fma_f32 v30, -v17, v245, v30
	v_fma_f32 v30, -v246, v18, v30
	v_fma_f32 v30, -v247, v19, v30
	ds_read_b128 v[214:217], v5 offset:25440
	s_waitcnt lgkmcnt(11)
	v_fma_f32 v30, -v232, v20, v30
	v_fma_f32 v30, -v233, v21, v30
	v_fma_f32 v30, -v234, v22, v30
	v_fma_f32 v23, -v23, v235, v30
	ds_read_b128 v[228:231], v5 offset:25664
	s_waitcnt lgkmcnt(11)
	v_fma_f32 v24, -v16, v146, v24
	v_fma_f32 v24, -v17, v147, v24
	v_fma_f32 v24, -v18, v148, v24
	v_fma_f32 v24, -v149, v19, v24
	ds_read_b128 v[244:247], v5 offset:25680
	s_waitcnt lgkmcnt(11)
	v_fma_f32 v24, -v150, v20, v24
	v_fma_f32 v24, -v151, v21, v24
	v_fma_f32 v24, -v152, v22, v24
	v_fma_f32 v24, -v153, v23, v24
	ds_read_b128 v[232:235], v5 offset:25696
	s_waitcnt lgkmcnt(11)
	v_fma_f32 v30, -v16, v182, v25
	v_fma_f32 v30, -v17, v183, v30
	v_fma_f32 v30, -v18, v184, v30
	v_fma_f32 v30, -v185, v19, v30
	ds_read_b128 v[146:149], v5 offset:25920
	s_waitcnt lgkmcnt(11)
	v_fma_f32 v30, -v178, v20, v30
	v_fma_f32 v30, -v179, v21, v30
	v_fma_f32 v30, -v180, v22, v30
	v_fma_f32 v30, -v181, v23, v30
	ds_read_b128 v[150:153], v5 offset:25936
	s_waitcnt lgkmcnt(11)
	v_fma_f32 v30, -v186, v24, v30
	v_fma_f32 v25, -v25, v187, v30
	v_fma_f32 v25, -v26, v188, v25
	v_fma_f32 v25, -v27, v189, v25
	ds_read_b128 v[182:185], v5 offset:25952
	s_waitcnt lgkmcnt(11)
	v_fma_f32 v30, -v16, v190, v26
	v_fma_f32 v30, -v17, v191, v30
	v_fma_f32 v30, -v18, v192, v30
	v_fma_f32 v30, -v19, v193, v30
	ds_read_b128 v[178:181], v5 offset:25968
	s_waitcnt lgkmcnt(11)
	v_fma_f32 v30, -v20, v198, v30
	v_fma_f32 v30, -v199, v21, v30
	v_fma_f32 v30, -v200, v22, v30
	v_fma_f32 v30, -v201, v23, v30
	ds_read_b128 v[186:189], v5 offset:26176
	s_waitcnt lgkmcnt(11)
	v_fma_f32 v30, -v194, v24, v30
	v_fma_f32 v30, -v195, v25, v30
	v_fma_f32 v26, -v26, v196, v30
	v_fma_f32 v26, -v27, v197, v26
	ds_read_b128 v[190:193], v5 offset:26192
	s_waitcnt lgkmcnt(11)
	v_fma_f32 v30, -v16, v206, v27
	v_fma_f32 v30, -v17, v207, v30
	v_fma_f32 v30, -v18, v208, v30
	v_fma_f32 v30, -v19, v209, v30
	ds_read_b128 v[198:201], v5 offset:26208
	s_waitcnt lgkmcnt(11)
	v_fma_f32 v30, -v20, v202, v30
	v_fma_f32 v30, -v203, v21, v30
	v_fma_f32 v30, -v204, v22, v30
	v_fma_f32 v30, -v205, v23, v30
	ds_read_b128 v[194:197], v5 offset:26224
	s_waitcnt lgkmcnt(11)
	v_fma_f32 v30, -v214, v24, v30
	v_fma_f32 v30, -v215, v25, v30
	v_fma_f32 v30, -v216, v26, v30
	v_fma_f32 v27, -v27, v217, v30
	ds_read_b128 v[206:209], v5 offset:26432
	s_waitcnt lgkmcnt(11)
	v_fma_f32 v28, -v16, v228, v28
	v_fma_f32 v28, -v17, v229, v28
	v_fma_f32 v28, -v18, v230, v28
	v_fma_f32 v28, -v19, v231, v28
	ds_read_b128 v[202:205], v5 offset:26448
	s_waitcnt lgkmcnt(11)
	v_fma_f32 v28, -v20, v244, v28
	v_fma_f32 v28, -v21, v245, v28
	v_fma_f32 v28, -v246, v22, v28
	v_fma_f32 v28, -v247, v23, v28
	ds_read_b128 v[214:217], v5 offset:26464
	s_waitcnt lgkmcnt(11)
	v_fma_f32 v28, -v232, v24, v28
	v_fma_f32 v28, -v233, v25, v28
	v_fma_f32 v28, -v234, v26, v28
	v_fma_f32 v28, -v235, v27, v28
	ds_read_b128 v[228:231], v5 offset:26480
	s_waitcnt lgkmcnt(11)
	v_fma_f32 v30, -v16, v146, v29
	v_fma_f32 v30, -v17, v147, v30
	v_fma_f32 v30, -v18, v148, v30
	v_fma_f32 v30, -v19, v149, v30
	ds_read_b128 v[244:247], v5 offset:26688
	s_waitcnt lgkmcnt(11)
	v_fma_f32 v30, -v20, v150, v30
	v_fma_f32 v30, -v21, v151, v30
	v_fma_f32 v30, -v22, v152, v30
	v_fma_f32 v30, -v153, v23, v30
	ds_read_b128 v[232:235], v5 offset:26704
	s_waitcnt lgkmcnt(11)
	v_fma_f32 v30, -v182, v24, v30
	v_fma_f32 v30, -v183, v25, v30
	v_fma_f32 v30, -v184, v26, v30
	v_fma_f32 v30, -v185, v27, v30
	ds_read_b128 v[146:149], v5 offset:26720
	s_waitcnt lgkmcnt(11)
	v_fma_f32 v30, -v178, v28, v30
	v_fma_f32 v29, -v29, v179, v30
	v_fma_f32 v29, -v72, v180, v29
	v_fma_f32 v29, -v32, v181, v29
	ds_read_b128 v[150:153], v5 offset:26736
	s_waitcnt lgkmcnt(11)
	v_fma_f32 v30, -v16, v186, v72
	v_fma_f32 v30, -v17, v187, v30
	v_fma_f32 v30, -v18, v188, v30
	v_fma_f32 v30, -v19, v189, v30
	ds_read_b128 v[182:185], v5 offset:26960
	s_waitcnt lgkmcnt(11)
	v_fma_f32 v30, -v20, v190, v30
	v_fma_f32 v30, -v21, v191, v30
	v_fma_f32 v30, -v22, v192, v30
	v_fma_f32 v30, -v23, v193, v30
	ds_read_b128 v[178:181], v5 offset:26944
	s_waitcnt lgkmcnt(11)
	v_fma_f32 v30, -v24, v198, v30
	v_fma_f32 v30, -v199, v25, v30
	v_fma_f32 v30, -v200, v26, v30
	v_fma_f32 v30, -v201, v27, v30
	ds_read_b128 v[186:189], v5 offset:26992
	s_waitcnt lgkmcnt(11)
	v_fma_f32 v30, -v194, v28, v30
	v_fma_f32 v30, -v195, v29, v30
	v_fma_f32 v30, -v72, v196, v30
	v_fma_f32 v30, -v32, v197, v30
	ds_read_b128 v[190:193], v5 offset:26976
	s_waitcnt lgkmcnt(11)
	v_fma_f32 v31, -v16, v206, v32
	v_fma_f32 v31, -v17, v207, v31
	v_fma_f32 v31, -v18, v208, v31
	v_fma_f32 v31, -v19, v209, v31
	ds_read_b128 v[198:201], v5 offset:27200
	s_waitcnt lgkmcnt(11)
	v_fma_f32 v31, -v20, v202, v31
	v_fma_f32 v31, -v21, v203, v31
	v_fma_f32 v31, -v22, v204, v31
	v_fma_f32 v31, -v23, v205, v31
	ds_read_b128 v[194:197], v5 offset:27216
	s_waitcnt lgkmcnt(11)
	v_fma_f32 v31, -v24, v214, v31
	v_fma_f32 v31, -v25, v215, v31
	v_fma_f32 v31, -v216, v26, v31
	v_fma_f32 v31, -v217, v27, v31
	ds_read_b128 v[206:209], v5 offset:27232
	s_waitcnt lgkmcnt(11)
	v_fma_f32 v31, -v228, v28, v31
	v_fma_f32 v31, -v229, v29, v31
	v_fma_f32 v31, -v230, v30, v31
	v_fma_f32 v31, -v32, v231, v31
	ds_read_b128 v[202:205], v5 offset:27248
	s_waitcnt lgkmcnt(11)
	v_fma_f32 v32, v16, v244, 0
	v_fma_f32 v88, v17, v245, 0
	v_fmac_f32_e32 v32, v18, v246
	v_fmac_f32_e32 v88, v19, v247
	ds_read_b128 v[214:217], v5 offset:27472
	s_waitcnt lgkmcnt(11)
	v_fmac_f32_e32 v32, v20, v232
	v_fmac_f32_e32 v88, v21, v233
	v_fmac_f32_e32 v32, v22, v234
	v_fmac_f32_e32 v88, v23, v235
	ds_read_b128 v[228:231], v5 offset:27456
	s_waitcnt lgkmcnt(11)
	v_fmac_f32_e32 v32, v24, v146
	v_fmac_f32_e32 v88, v25, v147
	v_fmac_f32_e32 v32, v26, v148
	v_fmac_f32_e32 v88, v149, v27
	ds_read_b128 v[244:247], v5 offset:27504
	s_waitcnt lgkmcnt(11)
	v_fmac_f32_e32 v32, v150, v28
	v_fmac_f32_e32 v88, v151, v29
	v_fmac_f32_e32 v32, v152, v30
	v_fmac_f32_e32 v88, v153, v31
	ds_read_b128 v[232:235], v5 offset:27488
	v_add_f32_e32 v32, v32, v88
	v_sub_f32_e32 v32, v33, v32
	s_waitcnt lgkmcnt(10)
	v_fma_f32 v33, v16, v178, 0
	v_fma_f32 v76, v17, v179, 0
	v_fmac_f32_e32 v33, v18, v180
	v_fmac_f32_e32 v76, v19, v181
	ds_read_b128 v[146:149], v5 offset:27712
	v_fmac_f32_e32 v33, v20, v182
	v_fmac_f32_e32 v76, v21, v183
	v_fmac_f32_e32 v33, v22, v184
	v_fmac_f32_e32 v76, v23, v185
	ds_read_b128 v[150:153], v5 offset:27728
	s_waitcnt lgkmcnt(10)
	v_fmac_f32_e32 v33, v24, v190
	v_fmac_f32_e32 v76, v25, v191
	v_fmac_f32_e32 v33, v26, v192
	v_fmac_f32_e32 v76, v27, v193
	ds_read_b128 v[178:181], v5 offset:27744
	v_fmac_f32_e32 v33, v186, v28
	v_fmac_f32_e32 v76, v187, v29
	v_fmac_f32_e32 v33, v188, v30
	v_fmac_f32_e32 v76, v189, v31
	ds_read_b128 v[182:185], v5 offset:27760
	v_add_f32_e32 v33, v33, v76
	v_sub_f32_e32 v33, v34, v33
	s_waitcnt lgkmcnt(11)
	v_fma_f32 v34, v16, v198, 0
	v_fma_f32 v88, v17, v199, 0
	v_fmac_f32_e32 v34, v18, v200
	v_fmac_f32_e32 v88, v19, v201
	ds_read_b128 v[190:193], v5 offset:27984
	s_waitcnt lgkmcnt(11)
	v_fmac_f32_e32 v34, v20, v194
	v_fmac_f32_e32 v88, v21, v195
	v_fmac_f32_e32 v34, v22, v196
	v_fmac_f32_e32 v88, v23, v197
	ds_read_b128 v[186:189], v5 offset:27968
	s_waitcnt lgkmcnt(11)
	v_fmac_f32_e32 v34, v24, v206
	v_fmac_f32_e32 v88, v25, v207
	v_fmac_f32_e32 v34, v26, v208
	v_fmac_f32_e32 v88, v27, v209
	ds_read_b128 v[198:201], v5 offset:28016
	s_waitcnt lgkmcnt(11)
	v_fmac_f32_e32 v34, v28, v202
	v_fmac_f32_e32 v88, v29, v203
	v_fmac_f32_e32 v34, v204, v30
	v_fmac_f32_e32 v88, v205, v31
	ds_read_b128 v[194:197], v5 offset:28000
	v_add_f32_e32 v34, v34, v88
	v_sub_f32_e32 v34, v35, v34
	s_waitcnt lgkmcnt(10)
	v_fma_f32 v35, v16, v228, 0
	v_fma_f32 v76, v17, v229, 0
	v_fmac_f32_e32 v35, v18, v230
	v_fmac_f32_e32 v76, v19, v231
	ds_read_b128 v[206:209], v5 offset:28224
	v_fmac_f32_e32 v35, v20, v214
	v_fmac_f32_e32 v76, v21, v215
	v_fmac_f32_e32 v35, v22, v216
	v_fmac_f32_e32 v76, v23, v217
	ds_read_b128 v[202:205], v5 offset:28240
	s_waitcnt lgkmcnt(10)
	v_fmac_f32_e32 v35, v24, v232
	v_fmac_f32_e32 v76, v25, v233
	v_fmac_f32_e32 v35, v26, v234
	v_fmac_f32_e32 v76, v27, v235
	ds_read_b128 v[228:231], v5 offset:28256
	v_fmac_f32_e32 v35, v28, v244
	v_fmac_f32_e32 v76, v29, v245
	v_fmac_f32_e32 v35, v246, v30
	v_fmac_f32_e32 v76, v247, v31
	ds_read_b128 v[214:217], v5 offset:28272
	v_add_f32_e32 v35, v35, v76
	v_sub_f32_e32 v35, v36, v35
	s_waitcnt lgkmcnt(11)
	v_fma_f32 v36, v16, v146, 0
	v_fma_f32 v88, v17, v147, 0
	v_fmac_f32_e32 v36, v18, v148
	v_fmac_f32_e32 v88, v19, v149
	ds_read_b128 v[232:235], v5 offset:28496
	s_waitcnt lgkmcnt(11)
	v_fmac_f32_e32 v36, v20, v150
	v_fmac_f32_e32 v88, v21, v151
	v_fmac_f32_e32 v36, v22, v152
	v_fmac_f32_e32 v88, v23, v153
	ds_read_b128 v[244:247], v5 offset:28480
	s_waitcnt lgkmcnt(11)
	v_fmac_f32_e32 v36, v24, v178
	v_fmac_f32_e32 v88, v25, v179
	v_fmac_f32_e32 v36, v26, v180
	v_fmac_f32_e32 v88, v27, v181
	ds_read_b128 v[146:149], v5 offset:28528
	s_waitcnt lgkmcnt(11)
	v_fmac_f32_e32 v36, v28, v182
	v_fmac_f32_e32 v88, v29, v183
	v_fmac_f32_e32 v36, v30, v184
	v_fmac_f32_e32 v88, v31, v185
	ds_read_b128 v[150:153], v5 offset:28512
	v_add_f32_e32 v36, v36, v88
	v_sub_f32_e32 v36, v37, v36
	s_waitcnt lgkmcnt(10)
	v_fma_f32 v37, v16, v186, 0
	v_fma_f32 v76, v17, v187, 0
	v_fmac_f32_e32 v37, v18, v188
	v_fmac_f32_e32 v76, v19, v189
	ds_read_b128 v[178:181], v5 offset:28736
	v_fmac_f32_e32 v37, v20, v190
	v_fmac_f32_e32 v76, v21, v191
	v_fmac_f32_e32 v37, v22, v192
	v_fmac_f32_e32 v76, v23, v193
	ds_read_b128 v[182:185], v5 offset:28752
	s_waitcnt lgkmcnt(10)
	v_fmac_f32_e32 v37, v24, v194
	v_fmac_f32_e32 v76, v25, v195
	v_fmac_f32_e32 v37, v26, v196
	v_fmac_f32_e32 v76, v27, v197
	ds_read_b128 v[186:189], v5 offset:28768
	v_fmac_f32_e32 v37, v28, v198
	v_fmac_f32_e32 v76, v29, v199
	v_fmac_f32_e32 v37, v30, v200
	v_fmac_f32_e32 v76, v31, v201
	ds_read_b128 v[190:193], v5 offset:28784
	v_add_f32_e32 v37, v37, v76
	v_sub_f32_e32 v37, v38, v37
	s_waitcnt lgkmcnt(11)
	v_fma_f32 v38, v16, v206, 0
	v_fma_f32 v88, v17, v207, 0
	v_fmac_f32_e32 v38, v18, v208
	v_fmac_f32_e32 v88, v19, v209
	ds_read_b128 v[194:197], v5 offset:29008
	s_waitcnt lgkmcnt(11)
	v_fmac_f32_e32 v38, v20, v202
	v_fmac_f32_e32 v88, v21, v203
	v_fmac_f32_e32 v38, v22, v204
	v_fmac_f32_e32 v88, v23, v205
	ds_read_b128 v[198:201], v5 offset:28992
	s_waitcnt lgkmcnt(11)
	v_fmac_f32_e32 v38, v24, v228
	v_fmac_f32_e32 v88, v25, v229
	v_fmac_f32_e32 v38, v26, v230
	v_fmac_f32_e32 v88, v27, v231
	ds_read_b128 v[206:209], v5 offset:29040
	s_waitcnt lgkmcnt(11)
	v_fmac_f32_e32 v38, v28, v214
	v_fmac_f32_e32 v88, v29, v215
	v_fmac_f32_e32 v38, v30, v216
	v_fmac_f32_e32 v88, v31, v217
	ds_read_b128 v[202:205], v5 offset:29024
	v_add_f32_e32 v38, v38, v88
	v_sub_f32_e32 v38, v39, v38
	s_waitcnt lgkmcnt(10)
	v_fma_f32 v39, v16, v244, 0
	v_fma_f32 v76, v17, v245, 0
	v_fmac_f32_e32 v39, v18, v246
	v_fmac_f32_e32 v76, v19, v247
	ds_read_b128 v[228:231], v5 offset:29248
	v_fmac_f32_e32 v39, v20, v232
	v_fmac_f32_e32 v76, v21, v233
	v_fmac_f32_e32 v39, v22, v234
	v_fmac_f32_e32 v76, v23, v235
	ds_read_b128 v[214:217], v5 offset:29264
	s_waitcnt lgkmcnt(10)
	v_fmac_f32_e32 v39, v24, v150
	v_fmac_f32_e32 v76, v25, v151
	v_fmac_f32_e32 v39, v26, v152
	v_fmac_f32_e32 v76, v27, v153
	ds_read_b128 v[244:247], v5 offset:29280
	v_fmac_f32_e32 v39, v28, v146
	v_fmac_f32_e32 v76, v29, v147
	v_fmac_f32_e32 v39, v30, v148
	v_fmac_f32_e32 v76, v31, v149
	ds_read_b128 v[232:235], v5 offset:29296
	v_add_f32_e32 v39, v39, v76
	v_sub_f32_e32 v39, v40, v39
	s_waitcnt lgkmcnt(11)
	v_fma_f32 v40, v16, v178, 0
	v_fma_f32 v88, v17, v179, 0
	v_fmac_f32_e32 v40, v18, v180
	v_fmac_f32_e32 v88, v19, v181
	ds_read_b128 v[150:153], v5 offset:29520
	s_waitcnt lgkmcnt(11)
	v_fmac_f32_e32 v40, v20, v182
	v_fmac_f32_e32 v88, v21, v183
	v_fmac_f32_e32 v40, v22, v184
	v_fmac_f32_e32 v88, v23, v185
	ds_read_b128 v[146:149], v5 offset:29504
	s_waitcnt lgkmcnt(11)
	v_fmac_f32_e32 v40, v24, v186
	v_fmac_f32_e32 v88, v25, v187
	v_fmac_f32_e32 v40, v26, v188
	v_fmac_f32_e32 v88, v27, v189
	ds_read_b128 v[178:181], v5 offset:29552
	s_waitcnt lgkmcnt(11)
	v_fmac_f32_e32 v40, v28, v190
	v_fmac_f32_e32 v88, v29, v191
	v_fmac_f32_e32 v40, v30, v192
	v_fmac_f32_e32 v88, v31, v193
	ds_read_b128 v[182:185], v5 offset:29536
	v_add_f32_e32 v40, v40, v88
	v_sub_f32_e32 v40, v41, v40
	s_waitcnt lgkmcnt(10)
	v_fma_f32 v41, v16, v198, 0
	v_fma_f32 v76, v17, v199, 0
	v_fmac_f32_e32 v41, v18, v200
	v_fmac_f32_e32 v76, v19, v201
	ds_read_b128 v[186:189], v5 offset:29760
	v_fmac_f32_e32 v41, v20, v194
	v_fmac_f32_e32 v76, v21, v195
	v_fmac_f32_e32 v41, v22, v196
	v_fmac_f32_e32 v76, v23, v197
	ds_read_b128 v[190:193], v5 offset:29776
	s_waitcnt lgkmcnt(10)
	v_fmac_f32_e32 v41, v24, v202
	v_fmac_f32_e32 v76, v25, v203
	v_fmac_f32_e32 v41, v26, v204
	v_fmac_f32_e32 v76, v27, v205
	ds_read_b128 v[198:201], v5 offset:29792
	v_fmac_f32_e32 v41, v28, v206
	v_fmac_f32_e32 v76, v29, v207
	v_fmac_f32_e32 v41, v30, v208
	v_fmac_f32_e32 v76, v31, v209
	ds_read_b128 v[194:197], v5 offset:29808
	v_add_f32_e32 v41, v41, v76
	v_sub_f32_e32 v41, v42, v41
	s_waitcnt lgkmcnt(11)
	v_fma_f32 v42, v16, v228, 0
	v_fma_f32 v88, v17, v229, 0
	v_fmac_f32_e32 v42, v18, v230
	v_fmac_f32_e32 v88, v19, v231
	ds_read_b128 v[202:205], v5 offset:30032
	s_waitcnt lgkmcnt(11)
	v_fmac_f32_e32 v42, v20, v214
	v_fmac_f32_e32 v88, v21, v215
	v_fmac_f32_e32 v42, v22, v216
	v_fmac_f32_e32 v88, v23, v217
	ds_read_b128 v[206:209], v5 offset:30016
	s_waitcnt lgkmcnt(11)
	v_fmac_f32_e32 v42, v24, v244
	v_fmac_f32_e32 v88, v25, v245
	v_fmac_f32_e32 v42, v26, v246
	v_fmac_f32_e32 v88, v27, v247
	ds_read_b128 v[228:231], v5 offset:30064
	s_waitcnt lgkmcnt(11)
	v_fmac_f32_e32 v42, v28, v232
	v_fmac_f32_e32 v88, v29, v233
	v_fmac_f32_e32 v42, v30, v234
	v_fmac_f32_e32 v88, v31, v235
	ds_read_b128 v[214:217], v5 offset:30048
	v_add_f32_e32 v42, v42, v88
	v_sub_f32_e32 v42, v43, v42
	s_waitcnt lgkmcnt(10)
	v_fma_f32 v43, v16, v146, 0
	v_fma_f32 v76, v17, v147, 0
	v_fmac_f32_e32 v43, v18, v148
	v_fmac_f32_e32 v76, v19, v149
	ds_read_b128 v[244:247], v5 offset:30272
	v_fmac_f32_e32 v43, v20, v150
	v_fmac_f32_e32 v76, v21, v151
	v_fmac_f32_e32 v43, v22, v152
	v_fmac_f32_e32 v76, v23, v153
	ds_read_b128 v[232:235], v5 offset:30288
	s_waitcnt lgkmcnt(10)
	v_fmac_f32_e32 v43, v24, v182
	v_fmac_f32_e32 v76, v25, v183
	v_fmac_f32_e32 v43, v26, v184
	v_fmac_f32_e32 v76, v27, v185
	ds_read_b128 v[146:149], v5 offset:30304
	v_fmac_f32_e32 v43, v28, v178
	v_fmac_f32_e32 v76, v29, v179
	v_fmac_f32_e32 v43, v30, v180
	v_fmac_f32_e32 v76, v31, v181
	ds_read_b128 v[150:153], v5 offset:30320
	v_add_f32_e32 v43, v43, v76
	v_sub_f32_e32 v43, v44, v43
	s_waitcnt lgkmcnt(11)
	v_fma_f32 v44, v16, v186, 0
	v_fma_f32 v88, v17, v187, 0
	v_fmac_f32_e32 v44, v18, v188
	v_fmac_f32_e32 v88, v19, v189
	ds_read_b128 v[182:185], v5 offset:30544
	s_waitcnt lgkmcnt(11)
	v_fmac_f32_e32 v44, v20, v190
	v_fmac_f32_e32 v88, v21, v191
	v_fmac_f32_e32 v44, v22, v192
	v_fmac_f32_e32 v88, v23, v193
	ds_read_b128 v[178:181], v5 offset:30528
	s_waitcnt lgkmcnt(11)
	v_fmac_f32_e32 v44, v24, v198
	v_fmac_f32_e32 v88, v25, v199
	v_fmac_f32_e32 v44, v26, v200
	v_fmac_f32_e32 v88, v27, v201
	ds_read_b128 v[186:189], v5 offset:30576
	s_waitcnt lgkmcnt(11)
	v_fmac_f32_e32 v44, v28, v194
	v_fmac_f32_e32 v88, v29, v195
	v_fmac_f32_e32 v44, v30, v196
	v_fmac_f32_e32 v88, v31, v197
	ds_read_b128 v[190:193], v5 offset:30560
	v_add_f32_e32 v44, v44, v88
	v_sub_f32_e32 v44, v45, v44
	s_waitcnt lgkmcnt(10)
	v_fma_f32 v45, v16, v206, 0
	v_fma_f32 v76, v17, v207, 0
	v_fmac_f32_e32 v45, v18, v208
	v_fmac_f32_e32 v76, v19, v209
	ds_read_b128 v[198:201], v5 offset:30784
	v_fmac_f32_e32 v45, v20, v202
	v_fmac_f32_e32 v76, v21, v203
	v_fmac_f32_e32 v45, v22, v204
	v_fmac_f32_e32 v76, v23, v205
	ds_read_b128 v[194:197], v5 offset:30800
	s_waitcnt lgkmcnt(10)
	v_fmac_f32_e32 v45, v24, v214
	v_fmac_f32_e32 v76, v25, v215
	v_fmac_f32_e32 v45, v26, v216
	v_fmac_f32_e32 v76, v27, v217
	ds_read_b128 v[206:209], v5 offset:30816
	v_fmac_f32_e32 v45, v28, v228
	v_fmac_f32_e32 v76, v29, v229
	v_fmac_f32_e32 v45, v30, v230
	v_fmac_f32_e32 v76, v31, v231
	ds_read_b128 v[202:205], v5 offset:30832
	v_add_f32_e32 v45, v45, v76
	v_sub_f32_e32 v45, v46, v45
	s_waitcnt lgkmcnt(11)
	v_fma_f32 v46, v16, v244, 0
	v_fma_f32 v88, v17, v245, 0
	v_fmac_f32_e32 v46, v18, v246
	v_fmac_f32_e32 v88, v19, v247
	ds_read_b128 v[214:217], v5 offset:31056
	s_waitcnt lgkmcnt(11)
	v_fmac_f32_e32 v46, v20, v232
	v_fmac_f32_e32 v88, v21, v233
	v_fmac_f32_e32 v46, v22, v234
	v_fmac_f32_e32 v88, v23, v235
	ds_read_b128 v[228:231], v5 offset:31040
	s_waitcnt lgkmcnt(11)
	v_fmac_f32_e32 v46, v24, v146
	v_fmac_f32_e32 v88, v25, v147
	v_fmac_f32_e32 v46, v26, v148
	v_fmac_f32_e32 v88, v27, v149
	ds_read_b128 v[244:247], v5 offset:31088
	s_waitcnt lgkmcnt(11)
	v_fmac_f32_e32 v46, v28, v150
	v_fmac_f32_e32 v88, v29, v151
	v_fmac_f32_e32 v46, v30, v152
	v_fmac_f32_e32 v88, v31, v153
	ds_read_b128 v[232:235], v5 offset:31072
	v_add_f32_e32 v46, v46, v88
	v_sub_f32_e32 v46, v47, v46
	s_waitcnt lgkmcnt(10)
	v_fma_f32 v47, v16, v178, 0
	v_fma_f32 v76, v17, v179, 0
	v_fmac_f32_e32 v47, v18, v180
	v_fmac_f32_e32 v76, v19, v181
	ds_read_b128 v[146:149], v5 offset:31296
	v_fmac_f32_e32 v47, v20, v182
	v_fmac_f32_e32 v76, v21, v183
	v_fmac_f32_e32 v47, v22, v184
	v_fmac_f32_e32 v76, v23, v185
	ds_read_b128 v[150:153], v5 offset:31312
	s_waitcnt lgkmcnt(10)
	v_fmac_f32_e32 v47, v24, v190
	v_fmac_f32_e32 v76, v25, v191
	v_fmac_f32_e32 v47, v26, v192
	v_fmac_f32_e32 v76, v27, v193
	ds_read_b128 v[178:181], v5 offset:31328
	v_fmac_f32_e32 v47, v28, v186
	v_fmac_f32_e32 v76, v29, v187
	v_fmac_f32_e32 v47, v30, v188
	v_fmac_f32_e32 v76, v31, v189
	ds_read_b128 v[182:185], v5 offset:31344
	v_add_f32_e32 v47, v47, v76
	v_sub_f32_e32 v47, v48, v47
	s_waitcnt lgkmcnt(11)
	v_fma_f32 v48, v16, v198, 0
	v_fma_f32 v88, v17, v199, 0
	v_fmac_f32_e32 v48, v18, v200
	v_fmac_f32_e32 v88, v19, v201
	ds_read_b128 v[190:193], v5 offset:31568
	s_waitcnt lgkmcnt(11)
	v_fmac_f32_e32 v48, v20, v194
	v_fmac_f32_e32 v88, v21, v195
	v_fmac_f32_e32 v48, v22, v196
	v_fmac_f32_e32 v88, v23, v197
	ds_read_b128 v[186:189], v5 offset:31552
	s_waitcnt lgkmcnt(11)
	v_fmac_f32_e32 v48, v24, v206
	v_fmac_f32_e32 v88, v25, v207
	v_fmac_f32_e32 v48, v26, v208
	v_fmac_f32_e32 v88, v27, v209
	ds_read_b128 v[198:201], v5 offset:31600
	s_waitcnt lgkmcnt(11)
	v_fmac_f32_e32 v48, v28, v202
	v_fmac_f32_e32 v88, v29, v203
	v_fmac_f32_e32 v48, v30, v204
	v_fmac_f32_e32 v88, v31, v205
	ds_read_b128 v[194:197], v5 offset:31584
	v_add_f32_e32 v48, v48, v88
	v_sub_f32_e32 v48, v49, v48
	s_waitcnt lgkmcnt(10)
	v_fma_f32 v49, v16, v228, 0
	v_fma_f32 v76, v17, v229, 0
	v_fmac_f32_e32 v49, v18, v230
	v_fmac_f32_e32 v76, v19, v231
	ds_read_b128 v[206:209], v5 offset:31808
	v_fmac_f32_e32 v49, v20, v214
	v_fmac_f32_e32 v76, v21, v215
	v_fmac_f32_e32 v49, v22, v216
	v_fmac_f32_e32 v76, v23, v217
	ds_read_b128 v[202:205], v5 offset:31824
	s_waitcnt lgkmcnt(10)
	v_fmac_f32_e32 v49, v24, v232
	v_fmac_f32_e32 v76, v25, v233
	v_fmac_f32_e32 v49, v26, v234
	v_fmac_f32_e32 v76, v27, v235
	ds_read_b128 v[228:231], v5 offset:31840
	v_fmac_f32_e32 v49, v28, v244
	v_fmac_f32_e32 v76, v29, v245
	v_fmac_f32_e32 v49, v30, v246
	v_fmac_f32_e32 v76, v31, v247
	ds_read_b128 v[214:217], v5 offset:31856
	v_add_f32_e32 v49, v49, v76
	v_sub_f32_e32 v49, v50, v49
	s_waitcnt lgkmcnt(11)
	v_fma_f32 v50, v16, v146, 0
	v_fma_f32 v88, v17, v147, 0
	v_fmac_f32_e32 v50, v18, v148
	v_fmac_f32_e32 v88, v19, v149
	ds_read_b128 v[232:235], v5 offset:32080
	s_waitcnt lgkmcnt(11)
	v_fmac_f32_e32 v50, v20, v150
	v_fmac_f32_e32 v88, v21, v151
	v_fmac_f32_e32 v50, v22, v152
	v_fmac_f32_e32 v88, v23, v153
	ds_read_b128 v[244:247], v5 offset:32064
	s_waitcnt lgkmcnt(11)
	v_fmac_f32_e32 v50, v24, v178
	v_fmac_f32_e32 v88, v25, v179
	v_fmac_f32_e32 v50, v26, v180
	v_fmac_f32_e32 v88, v27, v181
	ds_read_b128 v[146:149], v5 offset:32112
	s_waitcnt lgkmcnt(11)
	v_fmac_f32_e32 v50, v28, v182
	v_fmac_f32_e32 v88, v29, v183
	v_fmac_f32_e32 v50, v30, v184
	v_fmac_f32_e32 v88, v31, v185
	ds_read_b128 v[150:153], v5 offset:32096
	v_add_f32_e32 v50, v50, v88
	v_sub_f32_e32 v50, v51, v50
	s_waitcnt lgkmcnt(10)
	v_fma_f32 v51, v16, v186, 0
	v_fma_f32 v76, v17, v187, 0
	v_fmac_f32_e32 v51, v18, v188
	v_fmac_f32_e32 v76, v19, v189
	ds_read_b128 v[178:181], v5 offset:32320
	v_fmac_f32_e32 v51, v20, v190
	v_fmac_f32_e32 v76, v21, v191
	v_fmac_f32_e32 v51, v22, v192
	v_fmac_f32_e32 v76, v23, v193
	ds_read_b128 v[182:185], v5 offset:32336
	s_waitcnt lgkmcnt(10)
	v_fmac_f32_e32 v51, v24, v194
	v_fmac_f32_e32 v76, v25, v195
	v_fmac_f32_e32 v51, v26, v196
	v_fmac_f32_e32 v76, v27, v197
	ds_read_b128 v[186:189], v5 offset:32352
	v_fmac_f32_e32 v51, v28, v198
	v_fmac_f32_e32 v76, v29, v199
	v_fmac_f32_e32 v51, v30, v200
	v_fmac_f32_e32 v76, v31, v201
	ds_read_b128 v[190:193], v5 offset:32368
	v_add_f32_e32 v51, v51, v76
	v_sub_f32_e32 v51, v52, v51
	s_waitcnt lgkmcnt(11)
	v_fma_f32 v52, v16, v206, 0
	v_fma_f32 v88, v17, v207, 0
	v_fmac_f32_e32 v52, v18, v208
	v_fmac_f32_e32 v88, v19, v209
	ds_read_b128 v[194:197], v5 offset:32592
	s_waitcnt lgkmcnt(11)
	v_fmac_f32_e32 v52, v20, v202
	v_fmac_f32_e32 v88, v21, v203
	v_fmac_f32_e32 v52, v22, v204
	v_fmac_f32_e32 v88, v23, v205
	ds_read_b128 v[198:201], v5 offset:32576
	s_waitcnt lgkmcnt(11)
	v_fmac_f32_e32 v52, v24, v228
	v_fmac_f32_e32 v88, v25, v229
	v_fmac_f32_e32 v52, v26, v230
	v_fmac_f32_e32 v88, v27, v231
	ds_read_b128 v[206:209], v5 offset:32624
	s_waitcnt lgkmcnt(11)
	v_fmac_f32_e32 v52, v28, v214
	v_fmac_f32_e32 v88, v29, v215
	v_fmac_f32_e32 v52, v30, v216
	v_fmac_f32_e32 v88, v31, v217
	ds_read_b128 v[202:205], v5 offset:32608
	v_add_f32_e32 v52, v52, v88
	v_sub_f32_e32 v52, v53, v52
	s_waitcnt lgkmcnt(10)
	v_fma_f32 v53, v16, v244, 0
	v_fma_f32 v76, v17, v245, 0
	v_fmac_f32_e32 v53, v18, v246
	v_fmac_f32_e32 v76, v19, v247
	ds_read_b128 v[228:231], v5 offset:32832
	v_fmac_f32_e32 v53, v20, v232
	v_fmac_f32_e32 v76, v21, v233
	v_fmac_f32_e32 v53, v22, v234
	v_fmac_f32_e32 v76, v23, v235
	ds_read_b128 v[214:217], v5 offset:32848
	s_waitcnt lgkmcnt(10)
	v_fmac_f32_e32 v53, v24, v150
	v_fmac_f32_e32 v76, v25, v151
	v_fmac_f32_e32 v53, v26, v152
	v_fmac_f32_e32 v76, v27, v153
	ds_read_b128 v[244:247], v5 offset:32864
	v_fmac_f32_e32 v53, v28, v146
	v_fmac_f32_e32 v76, v29, v147
	v_fmac_f32_e32 v53, v30, v148
	v_fmac_f32_e32 v76, v31, v149
	ds_read_b128 v[232:235], v5 offset:32880
	v_add_f32_e32 v53, v53, v76
	v_sub_f32_e32 v53, v54, v53
	s_waitcnt lgkmcnt(11)
	v_fma_f32 v54, v16, v178, 0
	v_fma_f32 v88, v17, v179, 0
	v_fmac_f32_e32 v54, v18, v180
	v_fmac_f32_e32 v88, v19, v181
	ds_read_b128 v[150:153], v5 offset:33104
	s_waitcnt lgkmcnt(11)
	v_fmac_f32_e32 v54, v20, v182
	v_fmac_f32_e32 v88, v21, v183
	v_fmac_f32_e32 v54, v22, v184
	v_fmac_f32_e32 v88, v23, v185
	ds_read_b128 v[146:149], v5 offset:33088
	s_waitcnt lgkmcnt(11)
	v_fmac_f32_e32 v54, v24, v186
	v_fmac_f32_e32 v88, v25, v187
	v_fmac_f32_e32 v54, v26, v188
	v_fmac_f32_e32 v88, v27, v189
	ds_read_b128 v[178:181], v5 offset:33136
	s_waitcnt lgkmcnt(11)
	v_fmac_f32_e32 v54, v28, v190
	v_fmac_f32_e32 v88, v29, v191
	v_fmac_f32_e32 v54, v30, v192
	v_fmac_f32_e32 v88, v31, v193
	ds_read_b128 v[182:185], v5 offset:33120
	v_add_f32_e32 v54, v54, v88
	v_sub_f32_e32 v54, v55, v54
	s_waitcnt lgkmcnt(10)
	v_fma_f32 v55, v16, v198, 0
	v_fma_f32 v76, v17, v199, 0
	v_fmac_f32_e32 v55, v18, v200
	v_fmac_f32_e32 v76, v19, v201
	ds_read_b128 v[186:189], v5 offset:33344
	v_fmac_f32_e32 v55, v20, v194
	v_fmac_f32_e32 v76, v21, v195
	v_fmac_f32_e32 v55, v22, v196
	v_fmac_f32_e32 v76, v23, v197
	ds_read_b128 v[190:193], v5 offset:33360
	s_waitcnt lgkmcnt(10)
	v_fmac_f32_e32 v55, v24, v202
	v_fmac_f32_e32 v76, v25, v203
	v_fmac_f32_e32 v55, v26, v204
	v_fmac_f32_e32 v76, v27, v205
	ds_read_b128 v[198:201], v5 offset:33376
	v_fmac_f32_e32 v55, v28, v206
	v_fmac_f32_e32 v76, v29, v207
	v_fmac_f32_e32 v55, v30, v208
	v_fmac_f32_e32 v76, v31, v209
	ds_read_b128 v[194:197], v5 offset:33392
	v_add_f32_e32 v55, v55, v76
	v_sub_f32_e32 v55, v56, v55
	s_waitcnt lgkmcnt(11)
	v_fma_f32 v56, v16, v228, 0
	v_fma_f32 v88, v17, v229, 0
	v_fmac_f32_e32 v56, v18, v230
	v_fmac_f32_e32 v88, v19, v231
	ds_read_b128 v[202:205], v5 offset:33616
	s_waitcnt lgkmcnt(11)
	v_fmac_f32_e32 v56, v20, v214
	v_fmac_f32_e32 v88, v21, v215
	v_fmac_f32_e32 v56, v22, v216
	v_fmac_f32_e32 v88, v23, v217
	ds_read_b128 v[206:209], v5 offset:33600
	s_waitcnt lgkmcnt(11)
	v_fmac_f32_e32 v56, v24, v244
	v_fmac_f32_e32 v88, v25, v245
	v_fmac_f32_e32 v56, v26, v246
	v_fmac_f32_e32 v88, v27, v247
	ds_read_b128 v[228:231], v5 offset:33648
	s_waitcnt lgkmcnt(11)
	v_fmac_f32_e32 v56, v28, v232
	v_fmac_f32_e32 v88, v29, v233
	v_fmac_f32_e32 v56, v30, v234
	v_fmac_f32_e32 v88, v31, v235
	ds_read_b128 v[214:217], v5 offset:33632
	v_add_f32_e32 v56, v56, v88
	v_sub_f32_e32 v56, v57, v56
	s_waitcnt lgkmcnt(10)
	v_fma_f32 v57, v16, v146, 0
	v_fma_f32 v76, v17, v147, 0
	v_fmac_f32_e32 v57, v18, v148
	v_fmac_f32_e32 v76, v19, v149
	ds_read_b128 v[244:247], v5 offset:33856
	v_fmac_f32_e32 v57, v20, v150
	v_fmac_f32_e32 v76, v21, v151
	v_fmac_f32_e32 v57, v22, v152
	v_fmac_f32_e32 v76, v23, v153
	ds_read_b128 v[232:235], v5 offset:33872
	s_waitcnt lgkmcnt(10)
	v_fmac_f32_e32 v57, v24, v182
	v_fmac_f32_e32 v76, v25, v183
	v_fmac_f32_e32 v57, v26, v184
	v_fmac_f32_e32 v76, v27, v185
	ds_read_b128 v[146:149], v5 offset:33888
	v_fmac_f32_e32 v57, v28, v178
	v_fmac_f32_e32 v76, v29, v179
	v_fmac_f32_e32 v57, v30, v180
	v_fmac_f32_e32 v76, v31, v181
	ds_read_b128 v[150:153], v5 offset:33904
	v_add_f32_e32 v57, v57, v76
	v_sub_f32_e32 v57, v58, v57
	s_waitcnt lgkmcnt(11)
	v_fma_f32 v58, v16, v186, 0
	v_fma_f32 v88, v17, v187, 0
	v_fmac_f32_e32 v58, v18, v188
	v_fmac_f32_e32 v88, v19, v189
	ds_read_b128 v[182:185], v5 offset:34128
	s_waitcnt lgkmcnt(11)
	v_fmac_f32_e32 v58, v20, v190
	v_fmac_f32_e32 v88, v21, v191
	v_fmac_f32_e32 v58, v22, v192
	v_fmac_f32_e32 v88, v23, v193
	ds_read_b128 v[178:181], v5 offset:34112
	s_waitcnt lgkmcnt(11)
	v_fmac_f32_e32 v58, v24, v198
	v_fmac_f32_e32 v88, v25, v199
	v_fmac_f32_e32 v58, v26, v200
	v_fmac_f32_e32 v88, v27, v201
	ds_read_b128 v[186:189], v5 offset:34160
	s_waitcnt lgkmcnt(11)
	v_fmac_f32_e32 v58, v28, v194
	v_fmac_f32_e32 v88, v29, v195
	v_fmac_f32_e32 v58, v30, v196
	v_fmac_f32_e32 v88, v31, v197
	ds_read_b128 v[190:193], v5 offset:34144
	v_add_f32_e32 v58, v58, v88
	v_sub_f32_e32 v58, v59, v58
	s_waitcnt lgkmcnt(10)
	v_fma_f32 v59, v16, v206, 0
	v_fma_f32 v76, v17, v207, 0
	v_fmac_f32_e32 v59, v18, v208
	v_fmac_f32_e32 v76, v19, v209
	ds_read_b128 v[198:201], v5 offset:34368
	v_fmac_f32_e32 v59, v20, v202
	v_fmac_f32_e32 v76, v21, v203
	v_fmac_f32_e32 v59, v22, v204
	v_fmac_f32_e32 v76, v23, v205
	ds_read_b128 v[194:197], v5 offset:34384
	s_waitcnt lgkmcnt(10)
	v_fmac_f32_e32 v59, v24, v214
	v_fmac_f32_e32 v76, v25, v215
	v_fmac_f32_e32 v59, v26, v216
	v_fmac_f32_e32 v76, v27, v217
	ds_read_b128 v[206:209], v5 offset:34400
	v_fmac_f32_e32 v59, v28, v228
	v_fmac_f32_e32 v76, v29, v229
	v_fmac_f32_e32 v59, v30, v230
	v_fmac_f32_e32 v76, v31, v231
	ds_read_b128 v[202:205], v5 offset:34416
	v_add_f32_e32 v59, v59, v76
	v_sub_f32_e32 v59, v61, v59
	s_waitcnt lgkmcnt(11)
	v_fma_f32 v61, v16, v244, 0
	v_fma_f32 v88, v17, v245, 0
	v_fmac_f32_e32 v61, v18, v246
	v_fmac_f32_e32 v88, v19, v247
	ds_read_b128 v[214:217], v5 offset:34640
	s_waitcnt lgkmcnt(11)
	v_fmac_f32_e32 v61, v20, v232
	v_fmac_f32_e32 v88, v21, v233
	v_fmac_f32_e32 v61, v22, v234
	v_fmac_f32_e32 v88, v23, v235
	ds_read_b128 v[228:231], v5 offset:34624
	s_waitcnt lgkmcnt(11)
	v_fmac_f32_e32 v61, v24, v146
	v_fmac_f32_e32 v88, v25, v147
	v_fmac_f32_e32 v61, v26, v148
	v_fmac_f32_e32 v88, v27, v149
	ds_read_b128 v[244:247], v5 offset:34672
	s_waitcnt lgkmcnt(11)
	v_fmac_f32_e32 v61, v28, v150
	v_fmac_f32_e32 v88, v29, v151
	v_fmac_f32_e32 v61, v30, v152
	v_fmac_f32_e32 v88, v31, v153
	ds_read_b128 v[232:235], v5 offset:34656
	v_add_f32_e32 v61, v61, v88
	v_sub_f32_e32 v61, v62, v61
	s_waitcnt lgkmcnt(10)
	v_fma_f32 v62, v16, v178, 0
	v_fma_f32 v76, v17, v179, 0
	v_fmac_f32_e32 v62, v18, v180
	v_fmac_f32_e32 v76, v19, v181
	ds_read_b128 v[146:149], v5 offset:27008
	v_fmac_f32_e32 v62, v20, v182
	v_fmac_f32_e32 v76, v21, v183
	v_fmac_f32_e32 v62, v22, v184
	v_fmac_f32_e32 v76, v23, v185
	ds_read_b128 v[150:153], v5 offset:27264
	s_waitcnt lgkmcnt(10)
	v_fmac_f32_e32 v62, v24, v190
	v_fmac_f32_e32 v76, v25, v191
	v_fmac_f32_e32 v62, v26, v192
	v_fmac_f32_e32 v76, v27, v193
	ds_read_b128 v[178:181], v5 offset:27520
	v_fmac_f32_e32 v62, v28, v186
	v_fmac_f32_e32 v76, v29, v187
	v_fmac_f32_e32 v62, v30, v188
	v_fmac_f32_e32 v76, v31, v189
	ds_read_b128 v[182:185], v5 offset:27776
	v_add_f32_e32 v62, v62, v76
	v_sub_f32_e32 v62, v63, v62
	s_waitcnt lgkmcnt(11)
	v_fma_f32 v63, v16, v198, 0
	v_fma_f32 v88, v17, v199, 0
	v_fmac_f32_e32 v63, v18, v200
	v_fmac_f32_e32 v88, v19, v201
	ds_read_b128 v[190:193], v5 offset:28032
	s_waitcnt lgkmcnt(11)
	v_fmac_f32_e32 v63, v20, v194
	v_fmac_f32_e32 v88, v21, v195
	v_fmac_f32_e32 v63, v22, v196
	v_fmac_f32_e32 v88, v23, v197
	ds_read_b128 v[186:189], v5 offset:28048
	s_waitcnt lgkmcnt(11)
	v_fmac_f32_e32 v63, v24, v206
	v_fmac_f32_e32 v88, v25, v207
	v_fmac_f32_e32 v63, v26, v208
	v_fmac_f32_e32 v88, v27, v209
	ds_read_b128 v[198:201], v5 offset:28288
	s_waitcnt lgkmcnt(11)
	v_fmac_f32_e32 v63, v28, v202
	v_fmac_f32_e32 v88, v29, v203
	v_fmac_f32_e32 v63, v30, v204
	v_fmac_f32_e32 v88, v31, v205
	ds_read_b128 v[194:197], v5 offset:28304
	v_add_f32_e32 v63, v63, v88
	v_sub_f32_e32 v63, v70, v63
	s_waitcnt lgkmcnt(10)
	v_fma_f32 v70, v16, v228, 0
	v_fma_f32 v76, v17, v229, 0
	v_fmac_f32_e32 v70, v18, v230
	v_fmac_f32_e32 v76, v19, v231
	ds_read_b128 v[206:209], v5 offset:28544
	v_fmac_f32_e32 v70, v20, v214
	v_fmac_f32_e32 v76, v21, v215
	v_fmac_f32_e32 v70, v22, v216
	v_fmac_f32_e32 v76, v23, v217
	ds_read_b128 v[202:205], v5 offset:28560
	s_waitcnt lgkmcnt(10)
	v_fmac_f32_e32 v70, v24, v232
	v_fmac_f32_e32 v76, v25, v233
	v_fmac_f32_e32 v70, v26, v234
	v_fmac_f32_e32 v76, v27, v235
	ds_read_b128 v[228:231], v5 offset:28800
	v_fmac_f32_e32 v70, v28, v244
	v_fmac_f32_e32 v76, v29, v245
	v_fmac_f32_e32 v70, v30, v246
	v_fmac_f32_e32 v76, v31, v247
	ds_read_b128 v[214:217], v5 offset:28816
	v_add_f32_e32 v70, v70, v76
	v_sub_f32_e32 v70, v71, v70
	s_waitcnt lgkmcnt(11)
	v_fma_f32 v71, -v32, v146, v33
	v_fma_f32 v33, -v33, v147, v71
	v_fma_f32 v33, -v34, v148, v33
	v_fma_f32 v33, -v35, v149, v33
	ds_read_b128 v[232:235], v5 offset:29056
	s_waitcnt lgkmcnt(11)
	v_fma_f32 v71, -v32, v150, v34
	v_fma_f32 v71, -v151, v33, v71
	v_fma_f32 v34, -v34, v152, v71
	v_fma_f32 v34, -v35, v153, v34
	ds_read_b128 v[244:247], v5 offset:29072
	s_waitcnt lgkmcnt(11)
	v_fma_f32 v71, -v32, v178, v35
	v_fma_f32 v71, -v179, v33, v71
	v_fma_f32 v71, -v180, v34, v71
	v_fma_f32 v35, -v35, v181, v71
	ds_read_b128 v[146:149], v5 offset:29088
	s_waitcnt lgkmcnt(11)
	v_fma_f32 v36, -v32, v182, v36
	v_fma_f32 v36, -v183, v33, v36
	v_fma_f32 v36, -v184, v34, v36
	v_fma_f32 v36, -v185, v35, v36
	ds_read_b128 v[150:153], v5 offset:29312
	s_waitcnt lgkmcnt(11)
	v_fma_f32 v71, -v32, v190, v37
	v_fma_f32 v71, -v191, v33, v71
	v_fma_f32 v71, -v192, v34, v71
	v_fma_f32 v71, -v193, v35, v71
	ds_read_b128 v[178:181], v5 offset:29328
	s_waitcnt lgkmcnt(11)
	v_fma_f32 v71, -v186, v36, v71
	v_fma_f32 v37, -v37, v187, v71
	v_fma_f32 v37, -v38, v188, v37
	v_fma_f32 v37, -v39, v189, v37
	ds_read_b128 v[182:185], v5 offset:29344
	s_waitcnt lgkmcnt(11)
	v_fma_f32 v71, -v32, v198, v38
	v_fma_f32 v71, -v33, v199, v71
	v_fma_f32 v71, -v200, v34, v71
	v_fma_f32 v71, -v201, v35, v71
	ds_read_b128 v[190:193], v5 offset:29568
	s_waitcnt lgkmcnt(11)
	v_fma_f32 v71, -v194, v36, v71
	v_fma_f32 v71, -v195, v37, v71
	v_fma_f32 v38, -v38, v196, v71
	v_fma_f32 v38, -v39, v197, v38
	ds_read_b128 v[186:189], v5 offset:29584
	s_waitcnt lgkmcnt(11)
	v_fma_f32 v71, -v32, v206, v39
	v_fma_f32 v71, -v33, v207, v71
	v_fma_f32 v71, -v208, v34, v71
	v_fma_f32 v71, -v209, v35, v71
	ds_read_b128 v[198:201], v5 offset:29600
	s_waitcnt lgkmcnt(11)
	v_fma_f32 v71, -v202, v36, v71
	v_fma_f32 v71, -v203, v37, v71
	v_fma_f32 v71, -v204, v38, v71
	v_fma_f32 v39, -v39, v205, v71
	ds_read_b128 v[194:197], v5 offset:29824
	s_waitcnt lgkmcnt(11)
	v_fma_f32 v40, -v32, v228, v40
	v_fma_f32 v40, -v33, v229, v40
	v_fma_f32 v40, -v34, v230, v40
	v_fma_f32 v40, -v231, v35, v40
	ds_read_b128 v[206:209], v5 offset:29840
	s_waitcnt lgkmcnt(11)
	v_fma_f32 v40, -v214, v36, v40
	v_fma_f32 v40, -v215, v37, v40
	v_fma_f32 v40, -v216, v38, v40
	v_fma_f32 v40, -v217, v39, v40
	ds_read_b128 v[202:205], v5 offset:29856
	s_waitcnt lgkmcnt(11)
	v_fma_f32 v71, -v32, v232, v41
	v_fma_f32 v71, -v33, v233, v71
	v_fma_f32 v71, -v34, v234, v71
	v_fma_f32 v71, -v235, v35, v71
	ds_read_b128 v[228:231], v5 offset:30080
	s_waitcnt lgkmcnt(11)
	v_fma_f32 v71, -v244, v36, v71
	v_fma_f32 v71, -v245, v37, v71
	v_fma_f32 v71, -v246, v38, v71
	v_fma_f32 v71, -v247, v39, v71
	ds_read_b128 v[214:217], v5 offset:30096
	s_waitcnt lgkmcnt(11)
	v_fma_f32 v71, -v146, v40, v71
	v_fma_f32 v41, -v41, v147, v71
	v_fma_f32 v41, -v42, v148, v41
	v_fma_f32 v41, -v43, v149, v41
	ds_read_b128 v[232:235], v5 offset:30112
	s_waitcnt lgkmcnt(11)
	v_fma_f32 v71, -v32, v150, v42
	v_fma_f32 v71, -v33, v151, v71
	v_fma_f32 v71, -v34, v152, v71
	v_fma_f32 v71, -v35, v153, v71
	ds_read_b128 v[244:247], v5 offset:30128
	s_waitcnt lgkmcnt(11)
	v_fma_f32 v71, -v36, v178, v71
	v_fma_f32 v71, -v179, v37, v71
	v_fma_f32 v71, -v180, v38, v71
	v_fma_f32 v71, -v181, v39, v71
	ds_read_b128 v[146:149], v5 offset:30336
	s_waitcnt lgkmcnt(11)
	v_fma_f32 v71, -v182, v40, v71
	v_fma_f32 v71, -v183, v41, v71
	v_fma_f32 v42, -v42, v184, v71
	v_fma_f32 v42, -v43, v185, v42
	ds_read_b128 v[150:153], v5 offset:30352
	s_waitcnt lgkmcnt(11)
	v_fma_f32 v71, -v32, v190, v43
	v_fma_f32 v71, -v33, v191, v71
	v_fma_f32 v71, -v34, v192, v71
	v_fma_f32 v71, -v35, v193, v71
	ds_read_b128 v[178:181], v5 offset:30368
	s_waitcnt lgkmcnt(11)
	v_fma_f32 v71, -v36, v186, v71
	v_fma_f32 v71, -v187, v37, v71
	v_fma_f32 v71, -v188, v38, v71
	v_fma_f32 v71, -v189, v39, v71
	ds_read_b128 v[182:185], v5 offset:30384
	s_waitcnt lgkmcnt(11)
	v_fma_f32 v71, -v198, v40, v71
	v_fma_f32 v71, -v199, v41, v71
	v_fma_f32 v71, -v200, v42, v71
	v_fma_f32 v43, -v43, v201, v71
	ds_read_b128 v[190:193], v5 offset:30592
	s_waitcnt lgkmcnt(11)
	v_fma_f32 v44, -v32, v194, v44
	v_fma_f32 v44, -v33, v195, v44
	v_fma_f32 v44, -v34, v196, v44
	v_fma_f32 v44, -v35, v197, v44
	ds_read_b128 v[186:189], v5 offset:30608
	s_waitcnt lgkmcnt(11)
	v_fma_f32 v44, -v36, v206, v44
	v_fma_f32 v44, -v37, v207, v44
	v_fma_f32 v44, -v208, v38, v44
	v_fma_f32 v44, -v209, v39, v44
	ds_read_b128 v[198:201], v5 offset:30624
	s_waitcnt lgkmcnt(11)
	v_fma_f32 v44, -v202, v40, v44
	v_fma_f32 v44, -v203, v41, v44
	v_fma_f32 v44, -v204, v42, v44
	v_fma_f32 v44, -v205, v43, v44
	ds_read_b128 v[194:197], v5 offset:30640
	s_waitcnt lgkmcnt(11)
	v_fma_f32 v71, -v32, v228, v45
	v_fma_f32 v71, -v33, v229, v71
	v_fma_f32 v71, -v34, v230, v71
	v_fma_f32 v71, -v35, v231, v71
	ds_read_b128 v[206:209], v5 offset:30848
	s_waitcnt lgkmcnt(11)
	v_fma_f32 v71, -v36, v214, v71
	v_fma_f32 v71, -v37, v215, v71
	v_fma_f32 v71, -v38, v216, v71
	v_fma_f32 v71, -v217, v39, v71
	ds_read_b128 v[202:205], v5 offset:30864
	s_waitcnt lgkmcnt(11)
	v_fma_f32 v71, -v232, v40, v71
	v_fma_f32 v71, -v233, v41, v71
	v_fma_f32 v71, -v234, v42, v71
	v_fma_f32 v71, -v235, v43, v71
	ds_read_b128 v[228:231], v5 offset:30880
	s_waitcnt lgkmcnt(11)
	v_fma_f32 v71, -v244, v44, v71
	v_fma_f32 v45, -v45, v245, v71
	v_fma_f32 v45, -v46, v246, v45
	v_fma_f32 v45, -v47, v247, v45
	ds_read_b128 v[214:217], v5 offset:30896
	s_waitcnt lgkmcnt(11)
	v_fma_f32 v71, -v32, v146, v46
	v_fma_f32 v71, -v33, v147, v71
	v_fma_f32 v71, -v34, v148, v71
	v_fma_f32 v71, -v35, v149, v71
	ds_read_b128 v[232:235], v5 offset:31120
	s_waitcnt lgkmcnt(11)
	v_fma_f32 v71, -v36, v150, v71
	v_fma_f32 v71, -v37, v151, v71
	v_fma_f32 v71, -v38, v152, v71
	v_fma_f32 v71, -v39, v153, v71
	ds_read_b128 v[244:247], v5 offset:31104
	s_waitcnt lgkmcnt(11)
	v_fma_f32 v71, -v40, v178, v71
	v_fma_f32 v71, -v179, v41, v71
	v_fma_f32 v71, -v180, v42, v71
	v_fma_f32 v71, -v181, v43, v71
	ds_read_b128 v[146:149], v5 offset:31152
	s_waitcnt lgkmcnt(11)
	v_fma_f32 v71, -v182, v44, v71
	v_fma_f32 v71, -v183, v45, v71
	v_fma_f32 v46, -v46, v184, v71
	v_fma_f32 v46, -v47, v185, v46
	ds_read_b128 v[150:153], v5 offset:31136
	s_waitcnt lgkmcnt(11)
	v_fma_f32 v71, -v32, v190, v47
	v_fma_f32 v71, -v33, v191, v71
	v_fma_f32 v71, -v34, v192, v71
	v_fma_f32 v71, -v35, v193, v71
	ds_read_b128 v[178:181], v5 offset:31360
	s_waitcnt lgkmcnt(11)
	v_fma_f32 v71, -v36, v186, v71
	v_fma_f32 v71, -v37, v187, v71
	v_fma_f32 v71, -v38, v188, v71
	v_fma_f32 v71, -v39, v189, v71
	ds_read_b128 v[182:185], v5 offset:31376
	s_waitcnt lgkmcnt(11)
	v_fma_f32 v71, -v40, v198, v71
	v_fma_f32 v71, -v41, v199, v71
	v_fma_f32 v71, -v200, v42, v71
	v_fma_f32 v71, -v201, v43, v71
	ds_read_b128 v[190:193], v5 offset:31392
	s_waitcnt lgkmcnt(11)
	v_fma_f32 v71, -v194, v44, v71
	v_fma_f32 v71, -v195, v45, v71
	v_fma_f32 v71, -v196, v46, v71
	v_fma_f32 v47, -v47, v197, v71
	ds_read_b128 v[186:189], v5 offset:31408
	s_waitcnt lgkmcnt(11)
	v_fma_f32 v71, v32, v206, 0
	v_fma_f32 v88, v33, v207, 0
	v_fmac_f32_e32 v71, v34, v208
	v_fmac_f32_e32 v88, v35, v209
	ds_read_b128 v[198:201], v5 offset:31632
	s_waitcnt lgkmcnt(11)
	v_fmac_f32_e32 v71, v36, v202
	v_fmac_f32_e32 v88, v37, v203
	v_fmac_f32_e32 v71, v38, v204
	v_fmac_f32_e32 v88, v39, v205
	ds_read_b128 v[194:197], v5 offset:31616
	s_waitcnt lgkmcnt(11)
	v_fmac_f32_e32 v71, v40, v228
	v_fmac_f32_e32 v88, v41, v229
	v_fmac_f32_e32 v71, v42, v230
	v_fmac_f32_e32 v88, v231, v43
	ds_read_b128 v[206:209], v5 offset:31664
	s_waitcnt lgkmcnt(11)
	v_fmac_f32_e32 v71, v214, v44
	v_fmac_f32_e32 v88, v215, v45
	v_fmac_f32_e32 v71, v216, v46
	v_fmac_f32_e32 v88, v217, v47
	ds_read_b128 v[202:205], v5 offset:31648
	v_add_f32_e32 v71, v71, v88
	v_sub_f32_e32 v48, v48, v71
	s_waitcnt lgkmcnt(10)
	v_fma_f32 v71, v32, v244, 0
	v_fma_f32 v76, v33, v245, 0
	v_fmac_f32_e32 v71, v34, v246
	v_fmac_f32_e32 v76, v35, v247
	ds_read_b128 v[228:231], v5 offset:31872
	v_fmac_f32_e32 v71, v36, v232
	v_fmac_f32_e32 v76, v37, v233
	v_fmac_f32_e32 v71, v38, v234
	v_fmac_f32_e32 v76, v39, v235
	ds_read_b128 v[214:217], v5 offset:31888
	s_waitcnt lgkmcnt(10)
	v_fmac_f32_e32 v71, v40, v150
	v_fmac_f32_e32 v76, v41, v151
	v_fmac_f32_e32 v71, v42, v152
	v_fmac_f32_e32 v76, v43, v153
	ds_read_b128 v[244:247], v5 offset:31904
	v_fmac_f32_e32 v71, v146, v44
	v_fmac_f32_e32 v76, v147, v45
	v_fmac_f32_e32 v71, v148, v46
	v_fmac_f32_e32 v76, v149, v47
	ds_read_b128 v[232:235], v5 offset:31920
	v_add_f32_e32 v71, v71, v76
	v_sub_f32_e32 v49, v49, v71
	s_waitcnt lgkmcnt(11)
	v_fma_f32 v71, v32, v178, 0
	v_fma_f32 v88, v33, v179, 0
	v_fmac_f32_e32 v71, v34, v180
	v_fmac_f32_e32 v88, v35, v181
	ds_read_b128 v[150:153], v5 offset:32144
	s_waitcnt lgkmcnt(11)
	v_fmac_f32_e32 v71, v36, v182
	v_fmac_f32_e32 v88, v37, v183
	v_fmac_f32_e32 v71, v38, v184
	v_fmac_f32_e32 v88, v39, v185
	ds_read_b128 v[146:149], v5 offset:32128
	s_waitcnt lgkmcnt(11)
	v_fmac_f32_e32 v71, v40, v190
	v_fmac_f32_e32 v88, v41, v191
	v_fmac_f32_e32 v71, v42, v192
	v_fmac_f32_e32 v88, v43, v193
	ds_read_b128 v[178:181], v5 offset:32176
	s_waitcnt lgkmcnt(11)
	v_fmac_f32_e32 v71, v44, v186
	v_fmac_f32_e32 v88, v45, v187
	v_fmac_f32_e32 v71, v188, v46
	v_fmac_f32_e32 v88, v189, v47
	ds_read_b128 v[182:185], v5 offset:32160
	v_add_f32_e32 v71, v71, v88
	v_sub_f32_e32 v50, v50, v71
	s_waitcnt lgkmcnt(10)
	v_fma_f32 v71, v32, v194, 0
	v_fma_f32 v76, v33, v195, 0
	v_fmac_f32_e32 v71, v34, v196
	v_fmac_f32_e32 v76, v35, v197
	ds_read_b128 v[190:193], v5 offset:32384
	v_fmac_f32_e32 v71, v36, v198
	v_fmac_f32_e32 v76, v37, v199
	v_fmac_f32_e32 v71, v38, v200
	v_fmac_f32_e32 v76, v39, v201
	ds_read_b128 v[186:189], v5 offset:32400
	s_waitcnt lgkmcnt(10)
	v_fmac_f32_e32 v71, v40, v202
	v_fmac_f32_e32 v76, v41, v203
	v_fmac_f32_e32 v71, v42, v204
	v_fmac_f32_e32 v76, v43, v205
	ds_read_b128 v[194:197], v5 offset:32416
	v_fmac_f32_e32 v71, v44, v206
	v_fmac_f32_e32 v76, v45, v207
	v_fmac_f32_e32 v71, v208, v46
	v_fmac_f32_e32 v76, v209, v47
	ds_read_b128 v[198:201], v5 offset:32432
	v_add_f32_e32 v71, v71, v76
	v_sub_f32_e32 v51, v51, v71
	s_waitcnt lgkmcnt(11)
	v_fma_f32 v71, v32, v228, 0
	v_fma_f32 v88, v33, v229, 0
	v_fmac_f32_e32 v71, v34, v230
	v_fmac_f32_e32 v88, v35, v231
	ds_read_b128 v[202:205], v5 offset:32656
	s_waitcnt lgkmcnt(11)
	v_fmac_f32_e32 v71, v36, v214
	v_fmac_f32_e32 v88, v37, v215
	v_fmac_f32_e32 v71, v38, v216
	v_fmac_f32_e32 v88, v39, v217
	ds_read_b128 v[206:209], v5 offset:32640
	s_waitcnt lgkmcnt(11)
	v_fmac_f32_e32 v71, v40, v244
	v_fmac_f32_e32 v88, v41, v245
	v_fmac_f32_e32 v71, v42, v246
	v_fmac_f32_e32 v88, v43, v247
	ds_read_b128 v[228:231], v5 offset:32688
	s_waitcnt lgkmcnt(11)
	v_fmac_f32_e32 v71, v44, v232
	v_fmac_f32_e32 v88, v45, v233
	v_fmac_f32_e32 v71, v46, v234
	v_fmac_f32_e32 v88, v47, v235
	ds_read_b128 v[214:217], v5 offset:32672
	v_add_f32_e32 v71, v71, v88
	v_sub_f32_e32 v52, v52, v71
	s_waitcnt lgkmcnt(10)
	v_fma_f32 v71, v32, v146, 0
	v_fma_f32 v76, v33, v147, 0
	v_fmac_f32_e32 v71, v34, v148
	v_fmac_f32_e32 v76, v35, v149
	ds_read_b128 v[244:247], v5 offset:32896
	v_fmac_f32_e32 v71, v36, v150
	v_fmac_f32_e32 v76, v37, v151
	v_fmac_f32_e32 v71, v38, v152
	v_fmac_f32_e32 v76, v39, v153
	ds_read_b128 v[232:235], v5 offset:32912
	s_waitcnt lgkmcnt(10)
	v_fmac_f32_e32 v71, v40, v182
	v_fmac_f32_e32 v76, v41, v183
	v_fmac_f32_e32 v71, v42, v184
	v_fmac_f32_e32 v76, v43, v185
	ds_read_b128 v[146:149], v5 offset:32928
	v_fmac_f32_e32 v71, v44, v178
	v_fmac_f32_e32 v76, v45, v179
	v_fmac_f32_e32 v71, v46, v180
	v_fmac_f32_e32 v76, v47, v181
	ds_read_b128 v[150:153], v5 offset:32944
	v_add_f32_e32 v71, v71, v76
	v_sub_f32_e32 v53, v53, v71
	s_waitcnt lgkmcnt(11)
	v_fma_f32 v71, v32, v190, 0
	v_fma_f32 v88, v33, v191, 0
	v_fmac_f32_e32 v71, v34, v192
	v_fmac_f32_e32 v88, v35, v193
	ds_read_b128 v[182:185], v5 offset:33168
	s_waitcnt lgkmcnt(11)
	v_fmac_f32_e32 v71, v36, v186
	v_fmac_f32_e32 v88, v37, v187
	v_fmac_f32_e32 v71, v38, v188
	v_fmac_f32_e32 v88, v39, v189
	ds_read_b128 v[178:181], v5 offset:33152
	s_waitcnt lgkmcnt(11)
	v_fmac_f32_e32 v71, v40, v194
	v_fmac_f32_e32 v88, v41, v195
	v_fmac_f32_e32 v71, v42, v196
	v_fmac_f32_e32 v88, v43, v197
	ds_read_b128 v[190:193], v5 offset:33200
	s_waitcnt lgkmcnt(11)
	v_fmac_f32_e32 v71, v44, v198
	v_fmac_f32_e32 v88, v45, v199
	v_fmac_f32_e32 v71, v46, v200
	v_fmac_f32_e32 v88, v47, v201
	ds_read_b128 v[186:189], v5 offset:33184
	v_add_f32_e32 v71, v71, v88
	v_sub_f32_e32 v77, v54, v71
	s_waitcnt lgkmcnt(10)
	v_fma_f32 v54, v32, v206, 0
	v_fma_f32 v71, v33, v207, 0
	v_fmac_f32_e32 v54, v34, v208
	v_fmac_f32_e32 v71, v35, v209
	ds_read_b128 v[194:197], v5 offset:33408
	v_fmac_f32_e32 v54, v36, v202
	v_fmac_f32_e32 v71, v37, v203
	v_fmac_f32_e32 v54, v38, v204
	v_fmac_f32_e32 v71, v39, v205
	ds_read_b128 v[198:201], v5 offset:33424
	s_waitcnt lgkmcnt(10)
	v_fmac_f32_e32 v54, v40, v214
	v_fmac_f32_e32 v71, v41, v215
	v_fmac_f32_e32 v54, v42, v216
	v_fmac_f32_e32 v71, v43, v217
	ds_read_b128 v[206:209], v5 offset:33440
	v_fmac_f32_e32 v54, v44, v228
	v_fmac_f32_e32 v71, v45, v229
	v_fmac_f32_e32 v54, v46, v230
	v_fmac_f32_e32 v71, v47, v231
	ds_read_b128 v[202:205], v5 offset:33456
	v_add_f32_e32 v54, v54, v71
	v_sub_f32_e32 v75, v55, v54
	s_waitcnt lgkmcnt(11)
	v_fma_f32 v54, v32, v244, 0
	v_fma_f32 v55, v33, v245, 0
	v_fmac_f32_e32 v54, v34, v246
	v_fmac_f32_e32 v55, v35, v247
	ds_read_b128 v[214:217], v5 offset:33680
	s_waitcnt lgkmcnt(11)
	v_fmac_f32_e32 v54, v36, v232
	v_fmac_f32_e32 v55, v37, v233
	v_fmac_f32_e32 v54, v38, v234
	v_fmac_f32_e32 v55, v39, v235
	ds_read_b128 v[228:231], v5 offset:33664
	s_waitcnt lgkmcnt(11)
	v_fmac_f32_e32 v54, v40, v146
	v_fmac_f32_e32 v55, v41, v147
	v_fmac_f32_e32 v54, v42, v148
	v_fmac_f32_e32 v55, v43, v149
	ds_read_b128 v[244:247], v5 offset:33712
	s_waitcnt lgkmcnt(11)
	v_fmac_f32_e32 v54, v44, v150
	v_fmac_f32_e32 v55, v45, v151
	v_fmac_f32_e32 v54, v46, v152
	v_fmac_f32_e32 v55, v47, v153
	ds_read_b128 v[232:235], v5 offset:33696
	v_add_f32_e32 v54, v54, v55
	v_sub_f32_e32 v76, v56, v54
	s_waitcnt lgkmcnt(10)
	v_fma_f32 v54, v32, v178, 0
	v_fma_f32 v55, v33, v179, 0
	v_fmac_f32_e32 v54, v34, v180
	v_fmac_f32_e32 v55, v35, v181
	ds_read_b128 v[146:149], v5 offset:33920
	v_fmac_f32_e32 v54, v36, v182
	v_fmac_f32_e32 v55, v37, v183
	v_fmac_f32_e32 v54, v38, v184
	v_fmac_f32_e32 v55, v39, v185
	ds_read_b128 v[150:153], v5 offset:33936
	s_waitcnt lgkmcnt(10)
	v_fmac_f32_e32 v54, v40, v186
	v_fmac_f32_e32 v55, v41, v187
	v_fmac_f32_e32 v54, v42, v188
	v_fmac_f32_e32 v55, v43, v189
	ds_read_b128 v[178:181], v5 offset:33952
	v_fmac_f32_e32 v54, v44, v190
	v_fmac_f32_e32 v55, v45, v191
	v_fmac_f32_e32 v54, v46, v192
	v_fmac_f32_e32 v55, v47, v193
	ds_read_b128 v[182:185], v5 offset:33968
	v_add_f32_e32 v54, v54, v55
	v_sub_f32_e32 v74, v57, v54
	s_waitcnt lgkmcnt(11)
	v_fma_f32 v71, v32, v194, 0
	v_fma_f32 v72, v33, v195, 0
	v_fmac_f32_e32 v71, v34, v196
	v_fmac_f32_e32 v72, v35, v197
	ds_read_b128 v[186:189], v5 offset:34192
	s_waitcnt lgkmcnt(11)
	v_fmac_f32_e32 v71, v36, v198
	v_fmac_f32_e32 v72, v37, v199
	v_fmac_f32_e32 v71, v38, v200
	v_fmac_f32_e32 v72, v39, v201
	ds_read_b128 v[190:193], v5 offset:34176
	s_waitcnt lgkmcnt(11)
	v_fmac_f32_e32 v71, v40, v206
	v_fmac_f32_e32 v72, v41, v207
	v_fmac_f32_e32 v71, v42, v208
	v_fmac_f32_e32 v72, v43, v209
	ds_read_b128 v[194:197], v5 offset:34224
	s_waitcnt lgkmcnt(11)
	v_fmac_f32_e32 v71, v44, v202
	v_fmac_f32_e32 v72, v45, v203
	v_fmac_f32_e32 v71, v46, v204
	v_fmac_f32_e32 v72, v47, v205
	ds_read_b128 v[198:201], v5 offset:34208
	v_add_f32_e32 v71, v71, v72
	v_sub_f32_e32 v73, v58, v71
	s_waitcnt lgkmcnt(10)
	v_fma_f32 v58, v32, v228, 0
	v_fma_f32 v71, v33, v229, 0
	v_fmac_f32_e32 v58, v34, v230
	v_fmac_f32_e32 v71, v35, v231
	ds_read_b128 v[206:209], v5 offset:34432
	v_fmac_f32_e32 v58, v36, v214
	v_fmac_f32_e32 v71, v37, v215
	v_fmac_f32_e32 v58, v38, v216
	v_fmac_f32_e32 v71, v39, v217
	ds_read_b128 v[202:205], v5 offset:34448
	s_waitcnt lgkmcnt(10)
	v_fmac_f32_e32 v58, v40, v232
	v_fmac_f32_e32 v71, v41, v233
	v_fmac_f32_e32 v58, v42, v234
	v_fmac_f32_e32 v71, v43, v235
	ds_read_b128 v[228:231], v5 offset:34464
	v_fmac_f32_e32 v58, v44, v244
	v_fmac_f32_e32 v71, v45, v245
	v_fmac_f32_e32 v58, v46, v246
	v_fmac_f32_e32 v71, v47, v247
	ds_read_b128 v[214:217], v5 offset:34480
	v_add_f32_e32 v54, v58, v71
	v_sub_f32_e32 v72, v59, v54
	s_waitcnt lgkmcnt(11)
	v_fma_f32 v58, v32, v146, 0
	v_fma_f32 v59, v33, v147, 0
	v_fmac_f32_e32 v58, v34, v148
	v_fmac_f32_e32 v59, v35, v149
	ds_read_b128 v[232:235], v5 offset:34704
	s_waitcnt lgkmcnt(11)
	v_fmac_f32_e32 v58, v36, v150
	v_fmac_f32_e32 v59, v37, v151
	v_fmac_f32_e32 v58, v38, v152
	v_fmac_f32_e32 v59, v39, v153
	ds_read_b128 v[244:247], v5 offset:34688
	ds_read_b128 v[146:149], v5 offset:34736
	ds_read_b128 v[150:153], v5 offset:34720
	s_waitcnt lgkmcnt(13)
	v_fmac_f32_e32 v58, v40, v178
	v_fmac_f32_e32 v59, v41, v179
	v_fmac_f32_e32 v58, v42, v180
	v_fmac_f32_e32 v59, v43, v181
	ds_read_b128 v[178:181], v5 offset:31168
	s_waitcnt lgkmcnt(13)
	v_fmac_f32_e32 v58, v44, v182
	v_fmac_f32_e32 v59, v45, v183
	v_fmac_f32_e32 v58, v46, v184
	v_fmac_f32_e32 v59, v47, v185
	ds_read_b128 v[182:185], v5 offset:31424
	v_add_f32_e32 v58, v58, v59
	v_sub_f32_e32 v71, v61, v58
	s_waitcnt lgkmcnt(12)
	v_fma_f32 v58, v32, v190, 0
	v_fma_f32 v59, v33, v191, 0
	v_fmac_f32_e32 v58, v34, v192
	v_fmac_f32_e32 v59, v35, v193
	ds_read_b128 v[190:193], v5 offset:31680
	v_fmac_f32_e32 v58, v36, v186
	v_fmac_f32_e32 v59, v37, v187
	v_fmac_f32_e32 v58, v38, v188
	v_fmac_f32_e32 v59, v39, v189
	ds_read_b128 v[186:189], v5 offset:31936
	s_waitcnt lgkmcnt(12)
	v_fmac_f32_e32 v58, v40, v198
	v_fmac_f32_e32 v59, v41, v199
	v_fmac_f32_e32 v58, v42, v200
	v_fmac_f32_e32 v59, v43, v201
	ds_read_b128 v[198:201], v5 offset:32192
	v_fmac_f32_e32 v58, v44, v194
	v_fmac_f32_e32 v59, v45, v195
	v_fmac_f32_e32 v58, v46, v196
	v_fmac_f32_e32 v59, v47, v197
	ds_read_b128 v[194:197], v5 offset:32208
	v_add_f32_e32 v54, v58, v59
	v_sub_f32_e32 v59, v62, v54
	s_waitcnt lgkmcnt(13)
	v_fma_f32 v54, v32, v206, 0
	v_fma_f32 v55, v33, v207, 0
	v_fmac_f32_e32 v54, v34, v208
	v_fmac_f32_e32 v55, v35, v209
	ds_read_b128 v[206:209], v5 offset:32448
	s_waitcnt lgkmcnt(13)
	v_fmac_f32_e32 v54, v36, v202
	v_fmac_f32_e32 v55, v37, v203
	v_fmac_f32_e32 v54, v38, v204
	v_fmac_f32_e32 v55, v39, v205
	ds_read_b128 v[202:205], v5 offset:32464
	s_waitcnt lgkmcnt(13)
	v_fmac_f32_e32 v54, v40, v228
	v_fmac_f32_e32 v55, v41, v229
	v_fmac_f32_e32 v54, v42, v230
	v_fmac_f32_e32 v55, v43, v231
	ds_read_b128 v[228:231], v5 offset:32704
	s_waitcnt lgkmcnt(13)
	v_fmac_f32_e32 v54, v44, v214
	v_fmac_f32_e32 v55, v45, v215
	v_fmac_f32_e32 v54, v46, v216
	v_fmac_f32_e32 v55, v47, v217
	ds_read_b128 v[214:217], v5 offset:32720
	v_add_f32_e32 v54, v54, v55
	v_sub_f32_e32 v57, v63, v54
	s_waitcnt lgkmcnt(12)
	v_fma_f32 v54, v32, v244, 0
	v_fma_f32 v55, v33, v245, 0
	v_fmac_f32_e32 v54, v34, v246
	v_fmac_f32_e32 v55, v35, v247
	v_fmac_f32_e32 v54, v36, v232
	v_fmac_f32_e32 v55, v37, v233
	v_fmac_f32_e32 v54, v38, v234
	v_fmac_f32_e32 v55, v39, v235
	ds_read_b128 v[232:235], v5 offset:32960
	s_waitcnt lgkmcnt(11)
	v_fmac_f32_e32 v54, v40, v150
	v_fmac_f32_e32 v55, v41, v151
	v_fmac_f32_e32 v54, v42, v152
	v_fmac_f32_e32 v55, v43, v153
	v_fmac_f32_e32 v54, v44, v146
	v_fmac_f32_e32 v55, v45, v147
	v_fmac_f32_e32 v54, v46, v148
	v_fmac_f32_e32 v55, v47, v149
	v_add_f32_e32 v54, v54, v55
	v_sub_f32_e32 v54, v70, v54
	s_waitcnt lgkmcnt(10)
	v_fma_f32 v55, -v48, v178, v49
	v_fma_f32 v49, -v49, v179, v55
	v_fma_f32 v49, -v50, v180, v49
	v_fma_f32 v49, -v51, v181, v49
	ds_read_b128 v[178:181], v5 offset:32976
	s_waitcnt lgkmcnt(10)
	v_fma_f32 v55, -v48, v182, v50
	v_fma_f32 v55, -v183, v49, v55
	v_fma_f32 v50, -v50, v184, v55
	v_fma_f32 v50, -v51, v185, v50
	ds_read_b128 v[182:185], v5 offset:33216
	s_waitcnt lgkmcnt(10)
	v_fma_f32 v55, -v48, v190, v51
	v_fma_f32 v55, -v191, v49, v55
	v_fma_f32 v55, -v192, v50, v55
	v_fma_f32 v51, -v51, v193, v55
	ds_read_b128 v[190:193], v5 offset:33232
	s_waitcnt lgkmcnt(10)
	v_fma_f32 v52, -v48, v186, v52
	v_fma_f32 v52, -v187, v49, v52
	v_fma_f32 v52, -v188, v50, v52
	v_fma_f32 v52, -v189, v51, v52
	ds_read_b128 v[186:189], v5 offset:33248
	s_waitcnt lgkmcnt(10)
	v_fma_f32 v55, -v48, v198, v53
	v_fma_f32 v55, -v199, v49, v55
	v_fma_f32 v55, -v200, v50, v55
	v_fma_f32 v55, -v201, v51, v55
	ds_read_b128 v[198:201], v5 offset:33472
	s_waitcnt lgkmcnt(10)
	v_fma_f32 v55, -v194, v52, v55
	v_fma_f32 v53, -v53, v195, v55
	v_fma_f32 v53, -v77, v196, v53
	v_fma_f32 v53, -v75, v197, v53
	ds_read_b128 v[194:197], v5 offset:33488
	s_waitcnt lgkmcnt(10)
	v_fma_f32 v55, -v48, v206, v77
	v_fma_f32 v55, -v49, v207, v55
	v_fma_f32 v55, -v208, v50, v55
	v_fma_f32 v55, -v209, v51, v55
	ds_read_b128 v[206:209], v5 offset:33504
	s_waitcnt lgkmcnt(10)
	v_fma_f32 v55, -v202, v52, v55
	v_fma_f32 v55, -v203, v53, v55
	v_fma_f32 v55, -v77, v204, v55
	v_fma_f32 v55, -v75, v205, v55
	ds_read_b128 v[202:205], v5 offset:33728
	s_waitcnt lgkmcnt(10)
	v_fma_f32 v56, -v48, v228, v75
	v_fma_f32 v56, -v49, v229, v56
	v_fma_f32 v56, -v230, v50, v56
	v_fma_f32 v56, -v231, v51, v56
	ds_read_b128 v[228:231], v5 offset:33744
	s_waitcnt lgkmcnt(10)
	v_fma_f32 v56, -v214, v52, v56
	v_fma_f32 v56, -v215, v53, v56
	v_fma_f32 v56, -v216, v55, v56
	v_fma_f32 v56, -v75, v217, v56
	ds_read_b128 v[214:217], v5 offset:33760
	s_waitcnt lgkmcnt(10)
	v_fma_f32 v58, -v48, v232, v76
	v_fma_f32 v58, -v49, v233, v58
	v_fma_f32 v58, -v50, v234, v58
	v_fma_f32 v58, -v235, v51, v58
	s_waitcnt lgkmcnt(9)
	v_fma_f32 v58, -v178, v52, v58
	v_fma_f32 v58, -v179, v53, v58
	v_fma_f32 v58, -v180, v55, v58
	v_fma_f32 v58, -v181, v56, v58
	ds_read_b128 v[178:181], v5 offset:33984
	s_waitcnt lgkmcnt(9)
	v_fma_f32 v61, -v48, v182, v74
	v_fma_f32 v61, -v49, v183, v61
	v_fma_f32 v61, -v50, v184, v61
	v_fma_f32 v61, -v185, v51, v61
	ds_read_b128 v[182:185], v5 offset:34000
	s_waitcnt lgkmcnt(9)
	v_fma_f32 v61, -v190, v52, v61
	v_fma_f32 v61, -v191, v53, v61
	v_fma_f32 v61, -v192, v55, v61
	v_fma_f32 v61, -v193, v56, v61
	ds_read_b128 v[190:193], v5 offset:34016
	s_waitcnt lgkmcnt(9)
	v_fma_f32 v61, -v186, v58, v61
	v_fma_f32 v61, -v74, v187, v61
	v_fma_f32 v61, -v73, v188, v61
	v_fma_f32 v61, -v72, v189, v61
	s_waitcnt lgkmcnt(8)
	v_fma_f32 v62, -v48, v198, v73
	v_fma_f32 v62, -v49, v199, v62
	v_fma_f32 v62, -v50, v200, v62
	v_fma_f32 v62, -v51, v201, v62
	ds_read_b128 v[198:201], v5 offset:34240
	s_waitcnt lgkmcnt(8)
	v_fma_f32 v62, -v52, v194, v62
	v_fma_f32 v62, -v195, v53, v62
	v_fma_f32 v62, -v196, v55, v62
	v_fma_f32 v62, -v197, v56, v62
	ds_read_b128 v[194:197], v5 offset:34256
	s_waitcnt lgkmcnt(8)
	v_fma_f32 v62, -v206, v58, v62
	v_fma_f32 v62, -v207, v61, v62
	v_fma_f32 v62, -v73, v208, v62
	v_fma_f32 v62, -v72, v209, v62
	ds_read_b128 v[206:209], v5 offset:34272
	s_waitcnt lgkmcnt(8)
	v_fma_f32 v63, -v48, v202, v72
	v_fma_f32 v63, -v49, v203, v63
	v_fma_f32 v63, -v50, v204, v63
	v_fma_f32 v63, -v51, v205, v63
	ds_read_b128 v[202:205], v5 offset:34288
	s_waitcnt lgkmcnt(8)
	v_fma_f32 v63, -v52, v228, v63
	v_fma_f32 v63, -v229, v53, v63
	v_fma_f32 v63, -v230, v55, v63
	v_fma_f32 v63, -v231, v56, v63
	ds_read_b128 v[228:231], v5 offset:34496
	s_waitcnt lgkmcnt(8)
	v_fma_f32 v63, -v214, v58, v63
	v_fma_f32 v63, -v215, v61, v63
	v_fma_f32 v63, -v216, v62, v63
	v_fma_f32 v63, -v72, v217, v63
	s_waitcnt lgkmcnt(7)
	v_fma_f32 v70, -v48, v178, v71
	v_fma_f32 v70, -v49, v179, v70
	v_fma_f32 v70, -v50, v180, v70
	v_fma_f32 v74, -v51, v181, v70
	ds_read_b128 v[178:181], v5 offset:34512
	s_waitcnt lgkmcnt(7)
	v_fma_f32 v70, -v52, v182, v74
	v_fma_f32 v70, -v53, v183, v70
	v_fma_f32 v70, -v184, v55, v70
	v_fma_f32 v74, -v185, v56, v70
	ds_read_b128 v[182:185], v5 offset:34528
	s_waitcnt lgkmcnt(7)
	v_fma_f32 v70, -v190, v58, v74
	v_fma_f32 v70, -v191, v61, v70
	v_fma_f32 v70, -v192, v62, v70
	v_fma_f32 v70, -v193, v63, v70
	ds_read_b128 v[190:193], v5 offset:34544
	s_waitcnt lgkmcnt(7)
	v_fma_f32 v71, -v48, v198, v59
	v_fma_f32 v71, -v49, v199, v71
	v_fma_f32 v71, -v50, v200, v71
	v_fma_f32 v71, -v51, v201, v71
	ds_read_b128 v[198:201], v5 offset:34752
	s_waitcnt lgkmcnt(7)
	v_fma_f32 v71, -v52, v194, v71
	v_fma_f32 v71, -v53, v195, v71
	v_fma_f32 v71, -v55, v196, v71
	v_fma_f32 v71, -v197, v56, v71
	ds_read_b128 v[194:197], v5 offset:34768
	s_waitcnt lgkmcnt(7)
	v_fma_f32 v71, -v206, v58, v71
	v_fma_f32 v71, -v207, v61, v71
	v_fma_f32 v71, -v208, v62, v71
	v_fma_f32 v71, -v209, v63, v71
	ds_read_b128 v[206:209], v5 offset:34784
	s_waitcnt lgkmcnt(7)
	v_fma_f32 v71, -v202, v70, v71
	v_fma_f32 v59, -v59, v203, v71
	v_fma_f32 v59, -v57, v204, v59
	v_fma_f32 v59, -v54, v205, v59
	ds_read_b128 v[202:205], v5 offset:34800
	s_waitcnt lgkmcnt(7)
	v_fma_f32 v71, -v48, v228, v57
	v_fma_f32 v71, -v49, v229, v71
	v_fma_f32 v71, -v50, v230, v71
	v_fma_f32 v71, -v51, v231, v71
	s_waitcnt lgkmcnt(6)
	v_fma_f32 v71, -v52, v178, v71
	v_fma_f32 v71, -v53, v179, v71
	v_fma_f32 v71, -v55, v180, v71
	v_fma_f32 v71, -v56, v181, v71
	s_waitcnt lgkmcnt(5)
	v_fma_f32 v71, -v58, v182, v71
	v_fma_f32 v71, -v183, v61, v71
	v_fma_f32 v71, -v184, v62, v71
	v_fma_f32 v71, -v185, v63, v71
	s_waitcnt lgkmcnt(4)
	v_fma_f32 v71, -v190, v70, v71
	v_fma_f32 v71, -v191, v59, v71
	v_fma_f32 v57, -v57, v192, v71
	v_fma_f32 v57, -v54, v193, v57
	s_waitcnt lgkmcnt(3)
	v_fma_f32 v71, -v48, v198, v54
	v_fma_f32 v71, -v49, v199, v71
	v_fma_f32 v71, -v50, v200, v71
	v_fma_f32 v71, -v51, v201, v71
	s_waitcnt lgkmcnt(2)
	v_fma_f32 v71, -v52, v194, v71
	v_fma_f32 v71, -v53, v195, v71
	v_fma_f32 v71, -v55, v196, v71
	v_fma_f32 v71, -v56, v197, v71
	s_waitcnt lgkmcnt(1)
	v_fma_f32 v71, -v58, v206, v71
	v_fma_f32 v71, -v61, v207, v71
	v_fma_f32 v71, -v208, v62, v71
	v_fma_f32 v71, -v209, v63, v71
	s_waitcnt lgkmcnt(0)
	v_fma_f32 v5, -v202, v70, v71
	v_fma_f32 v5, -v203, v59, v5
	v_fma_f32 v5, -v204, v57, v5
	v_fma_f32 v5, -v54, v205, v5
	v_mov_b32_e32 v72, v202
	v_mov_b32_e32 v73, v203
	v_mov_b32_e32 v74, v204
	v_mov_b32_e32 v75, v205
	v_mov_b32_e32 v76, v216
	v_mov_b32_e32 v77, v217
	v_mov_b32_e32 v78, v188
	v_mov_b32_e32 v79, v189
	v_mov_b32_e32 v80, v234
	v_mov_b32_e32 v81, v235
	v_mov_b32_e32 v82, v244
	v_mov_b32_e32 v83, v245
	v_mov_b32_e32 v84, v246
	v_mov_b32_e32 v85, v247
	v_mov_b32_e32 v86, v146
	v_mov_b32_e32 v87, v147
	v_mov_b32_e32 v88, v148
	v_mov_b32_e32 v89, v149
	v_mov_b32_e32 v90, v150
	v_mov_b32_e32 v91, v151
	v_mov_b32_e32 v92, v152
	v_mov_b32_e32 v93, v153
	v_readlane_b32 s16, v253, 32
	v_readlane_b32 s17, v253, 33
	s_mov_b64 s[12:13], -1
	s_and_b64 vcc, exec, s[16:17]
	s_cbranch_vccz .LBB0_811
	v_add_co_u32_e32 v74, vcc, 0x4000, v68
	v_cvt_pk_bf16_f32 v54, -v60, s0
	s_mov_b64 s[12:13], 0x4000
	v_addc_co_u32_e32 v75, vcc, 0, v69, vcc
	v_lshl_add_u64 v[72:73], v[68:69], 0, s[12:13]
	global_store_short v[74:75], v54, off
	v_cvt_pk_bf16_f32 v54, -v0, s0
	global_store_short v[72:73], v54, off offset:128
	v_cvt_pk_bf16_f32 v54, -v1, s0
	global_store_short v[72:73], v54, off offset:256
	v_cvt_pk_bf16_f32 v54, -v2, s0
	global_store_short v[72:73], v54, off offset:384
	v_cvt_pk_bf16_f32 v54, -v3, s0
	global_store_short v[72:73], v54, off offset:512
	v_cvt_pk_bf16_f32 v54, -v4, s0
	global_store_short v[72:73], v54, off offset:640
	v_cvt_pk_bf16_f32 v54, -v6, s0
	global_store_short v[72:73], v54, off offset:768
	v_cvt_pk_bf16_f32 v54, -v7, s0
	global_store_short v[72:73], v54, off offset:896
	v_cvt_pk_bf16_f32 v54, -v8, s0
	global_store_short v[72:73], v54, off offset:1024
	v_cvt_pk_bf16_f32 v54, -v9, s0
	global_store_short v[72:73], v54, off offset:1152
	v_cvt_pk_bf16_f32 v54, -v10, s0
	global_store_short v[72:73], v54, off offset:1280
	v_cvt_pk_bf16_f32 v54, -v11, s0
	global_store_short v[72:73], v54, off offset:1408
	v_cvt_pk_bf16_f32 v54, -v12, s0
	global_store_short v[72:73], v54, off offset:1536
	v_cvt_pk_bf16_f32 v54, -v13, s0
	global_store_short v[72:73], v54, off offset:1664
	v_cvt_pk_bf16_f32 v54, -v14, s0
	global_store_short v[72:73], v54, off offset:1792
	v_cvt_pk_bf16_f32 v54, -v15, s0
	global_store_short v[72:73], v54, off offset:1920
	v_cvt_pk_bf16_f32 v54, -v16, s0
	global_store_short v[72:73], v54, off offset:2048
	v_cvt_pk_bf16_f32 v54, -v17, s0
	global_store_short v[72:73], v54, off offset:2176
	v_cvt_pk_bf16_f32 v54, -v18, s0
	global_store_short v[72:73], v54, off offset:2304
	v_cvt_pk_bf16_f32 v54, -v19, s0
	global_store_short v[72:73], v54, off offset:2432
	v_cvt_pk_bf16_f32 v54, -v20, s0
	global_store_short v[72:73], v54, off offset:2560
	v_cvt_pk_bf16_f32 v54, -v21, s0
	global_store_short v[72:73], v54, off offset:2688
	v_cvt_pk_bf16_f32 v54, -v22, s0
	global_store_short v[72:73], v54, off offset:2816
	v_cvt_pk_bf16_f32 v54, -v23, s0
	global_store_short v[72:73], v54, off offset:2944
	v_cvt_pk_bf16_f32 v54, -v24, s0
	global_store_short v[72:73], v54, off offset:3072
	v_cvt_pk_bf16_f32 v54, -v25, s0
	global_store_short v[72:73], v54, off offset:3200
	v_cvt_pk_bf16_f32 v54, -v26, s0
	global_store_short v[72:73], v54, off offset:3328
	v_cvt_pk_bf16_f32 v54, -v27, s0
	global_store_short v[72:73], v54, off offset:3456
	v_cvt_pk_bf16_f32 v54, -v28, s0
	global_store_short v[72:73], v54, off offset:3584
	v_cvt_pk_bf16_f32 v54, -v29, s0
	global_store_short v[72:73], v54, off offset:3712
	v_cvt_pk_bf16_f32 v54, -v30, s0
	s_movk_i32 s6, 0x5000
	global_store_short v[72:73], v54, off offset:3840
	v_cvt_pk_bf16_f32 v54, -v31, s0
	v_add_co_u32_e32 v68, vcc, s6, v68
	global_store_short v[72:73], v54, off offset:3968
	v_cvt_pk_bf16_f32 v54, -v32, s0
	v_addc_co_u32_e32 v69, vcc, 0, v69, vcc
	global_store_short v[68:69], v54, off
	v_cvt_pk_bf16_f32 v54, -v33, s0
	global_store_short v[68:69], v54, off offset:128
	v_cvt_pk_bf16_f32 v54, -v34, s0
	global_store_short v[68:69], v54, off offset:256
	v_cvt_pk_bf16_f32 v54, -v35, s0
	global_store_short v[68:69], v54, off offset:384
	v_cvt_pk_bf16_f32 v54, -v36, s0
	global_store_short v[68:69], v54, off offset:512
	v_cvt_pk_bf16_f32 v54, -v37, s0
	global_store_short v[68:69], v54, off offset:640
	v_cvt_pk_bf16_f32 v54, -v38, s0
	global_store_short v[68:69], v54, off offset:768
	v_cvt_pk_bf16_f32 v54, -v39, s0
	global_store_short v[68:69], v54, off offset:896
	v_cvt_pk_bf16_f32 v54, -v40, s0
	global_store_short v[68:69], v54, off offset:1024
	v_cvt_pk_bf16_f32 v54, -v41, s0
	global_store_short v[68:69], v54, off offset:1152
	v_cvt_pk_bf16_f32 v54, -v42, s0
	global_store_short v[68:69], v54, off offset:1280
	v_cvt_pk_bf16_f32 v54, -v43, s0
	global_store_short v[68:69], v54, off offset:1408
	v_cvt_pk_bf16_f32 v54, -v44, s0
	global_store_short v[68:69], v54, off offset:1536
	v_cvt_pk_bf16_f32 v54, -v45, s0
	global_store_short v[68:69], v54, off offset:1664
	v_cvt_pk_bf16_f32 v54, -v46, s0
	global_store_short v[68:69], v54, off offset:1792
	v_cvt_pk_bf16_f32 v54, -v47, s0
	global_store_short v[68:69], v54, off offset:1920
	v_cvt_pk_bf16_f32 v54, -v48, s0
	global_store_short v[68:69], v54, off offset:2048
	v_cvt_pk_bf16_f32 v54, -v49, s0
	global_store_short v[68:69], v54, off offset:2176
	v_cvt_pk_bf16_f32 v54, -v50, s0
	global_store_short v[68:69], v54, off offset:2304
	v_cvt_pk_bf16_f32 v54, -v51, s0
	global_store_short v[68:69], v54, off offset:2432
	v_cvt_pk_bf16_f32 v54, -v52, s0
	global_store_short v[68:69], v54, off offset:2560
	v_cvt_pk_bf16_f32 v54, -v53, s0
	global_store_short v[68:69], v54, off offset:2688
	v_cvt_pk_bf16_f32 v54, -v55, s0
	global_store_short v[68:69], v54, off offset:2816
	v_cvt_pk_bf16_f32 v54, -v56, s0
	global_store_short v[68:69], v54, off offset:2944
	v_cvt_pk_bf16_f32 v54, -v58, s0
	global_store_short v[68:69], v54, off offset:3072
	v_cvt_pk_bf16_f32 v54, -v61, s0
	global_store_short v[68:69], v54, off offset:3200
	v_cvt_pk_bf16_f32 v54, -v62, s0
	global_store_short v[68:69], v54, off offset:3328
	v_cvt_pk_bf16_f32 v54, -v63, s0
	global_store_short v[68:69], v54, off offset:3456
	v_cvt_pk_bf16_f32 v54, -v70, s0
	global_store_short v[68:69], v54, off offset:3584
	v_cvt_pk_bf16_f32 v54, -v59, s0
	global_store_short v[68:69], v54, off offset:3712
	v_cvt_pk_bf16_f32 v54, -v57, s0
	global_store_short v[68:69], v54, off offset:3840
	v_cvt_pk_bf16_f32 v54, -v5, s0
	s_mov_b64 s[12:13], 0
	global_store_short v[68:69], v54, off offset:3968

.LBB0_1522:
	s_cmpk_gt_i32 s17, 0x1ff
	s_mov_b64 s[12:13], -1
	s_cbranch_scc0 .LBB0_1556
	v_readlane_b32 s12, v252, 16
	v_mbcnt_lo_u32_b32 v0, -1, 0
	v_mbcnt_hi_u32_b32 v0, -1, v0
	s_mov_b32 s6, s17
	s_mov_b32 s7, s12
	v_readlane_b32 s13, v252, 17
	v_lshl_add_u32 v2, s7, 6, v0
	v_ashrrev_i32_e32 v3, 31, v2
	v_lshl_add_u64 v[2:3], v[2:3], 2, s[52:53]
	global_load_dword v6, v[2:3], off
	v_mov_b32_e32 v76, 0
	v_mov_b32_e32 v77, 0
	v_mov_b32_e32 v78, 0
	v_mov_b32_e32 v79, 0
	v_mov_b32_e32 v80, 0
	v_mov_b32_e32 v81, 0
	v_mov_b32_e32 v82, 0
	v_mov_b32_e32 v83, 0
	v_mov_b32_e32 v84, 0
	v_mov_b32_e32 v85, 0
	v_mov_b32_e32 v86, 0
	v_mov_b32_e32 v87, 0
	v_mov_b32_e32 v88, 0
	v_mov_b32_e32 v89, 0
	v_mov_b32_e32 v90, 0
	v_mov_b32_e32 v91, 0
	v_mov_b32_e32 v92, 0
	v_mov_b32_e32 v93, 0
	v_mov_b32_e32 v94, 0
	v_mov_b32_e32 v95, 0
	v_mov_b32_e32 v96, 0
	v_mov_b32_e32 v97, 0
	v_mov_b32_e32 v98, 0
	v_mov_b32_e32 v99, 0
	v_mov_b32_e32 v100, 0
	v_mov_b32_e32 v101, 0
	v_mov_b32_e32 v102, 0
	v_mov_b32_e32 v103, 0
	v_mov_b32_e32 v104, 0
	v_mov_b32_e32 v105, 0
	v_mov_b32_e32 v108, 0
	v_mov_b32_e32 v109, 0
	s_lshl_b32 s7, s6, 4
	s_lshl_b32 s12, s6, 6
	s_add_i32 s13, s7, 0x6000
	s_cmpk_lt_i32 s6, 0x200
	s_cselect_b32 s7, 64, 16
	s_cselect_b32 s6, s12, s13
	v_ashrrev_i32_e32 v1, 31, v0
	s_cmp_lt_u32 s84, s7
	v_lshl_add_u64 v[2:3], v[0:1], 2, s[68:69]
	v_lshl_add_u64 v[4:5], v[0:1], 1, s[20:21]
	v_mov_b32_e32 v56, 0
	s_cselect_b64 s[38:39], -1, 0
	s_cmp_ge_u32 s84, s7
	v_mov_b32_e32 v66, 0
	v_mov_b32_e32 v67, 0
	v_mov_b32_e32 v70, 0
	v_mov_b32_e32 v71, 0
	s_cbranch_scc1 .LBB0_1525
	s_add_i32 s12, s6, s84
	s_ashr_i32 s13, s12, 31
	s_lshl_b64 s[40:41], s[12:13], 10
	v_mad_i64_i32 v[10:11], s[12:13], s12, v227, v[4:5]
	v_lshl_add_u64 v[8:9], v[2:3], 0, s[40:41]
	global_load_ushort v76, v[10:11], off
	global_load_ushort v77, v[10:11], off offset:128
	global_load_ushort v78, v[10:11], off offset:256
	s_nop 0
	global_load_ushort v79, v[10:11], off offset:384
	s_nop 0
	global_load_dword v69, v[8:9], off
	global_load_dword v68, v[8:9], off offset:256
	global_load_dword v65, v[8:9], off offset:512
	global_load_dword v62, v[8:9], off offset:768
.LBB0_1525:
	v_readlane_b32 s12, v254, 1
	s_cmp_lt_u32 s12, s7
	s_cselect_b64 s[80:81], -1, 0
	s_cmp_ge_u32 s12, s7
	v_mov_b32_e32 v58, 0
	v_mov_b32_e32 v61, 0
	v_mov_b32_e32 v63, 0
	s_cbranch_scc1 .LBB0_1527
	v_readlane_b32 s12, v254, 1
	s_add_i32 s12, s6, s12
	s_ashr_i32 s13, s12, 31
	s_lshl_b64 s[40:41], s[12:13], 10
	v_mad_i64_i32 v[10:11], s[12:13], s12, v227, v[4:5]
	v_lshl_add_u64 v[8:9], v[2:3], 0, s[40:41]
	global_load_ushort v80, v[10:11], off
	global_load_ushort v81, v[10:11], off offset:128
	global_load_ushort v82, v[10:11], off offset:256
	s_nop 0
	global_load_ushort v83, v[10:11], off offset:384
	s_nop 0
	global_load_dword v60, v[8:9], off
	global_load_dword v59, v[8:9], off offset:256
	global_load_dword v57, v[8:9], off offset:512
	global_load_dword v54, v[8:9], off offset:768
.LBB0_1527:
	v_readlane_b32 s12, v254, 2
	s_cmp_lt_u32 s12, s7
	v_mov_b32_e32 v40, 0
	s_cselect_b64 s[50:51], -1, 0
	s_cmp_ge_u32 s12, s7
	v_mov_b32_e32 v49, 0
	v_mov_b32_e32 v50, 0
	v_mov_b32_e32 v53, 0
	v_mov_b32_e32 v55, 0
	s_cbranch_scc1 .LBB0_1529
	v_readlane_b32 s12, v254, 2
	s_add_i32 s12, s6, s12
	s_ashr_i32 s13, s12, 31
	s_lshl_b64 s[40:41], s[12:13], 10
	v_mad_i64_i32 v[10:11], s[12:13], s12, v227, v[4:5]
	v_lshl_add_u64 v[8:9], v[2:3], 0, s[40:41]
	global_load_ushort v84, v[10:11], off
	global_load_ushort v85, v[10:11], off offset:128
	global_load_ushort v86, v[10:11], off offset:256
	s_nop 0
	global_load_ushort v87, v[10:11], off offset:384
	s_nop 0
	global_load_dword v52, v[8:9], off
	global_load_dword v51, v[8:9], off offset:256
	global_load_dword v48, v[8:9], off offset:512
	global_load_dword v46, v[8:9], off offset:768
.LBB0_1529:
	v_readlane_b32 s12, v254, 3
	s_cmp_lt_u32 s12, s7
	s_cselect_b64 s[48:49], -1, 0
	s_cmp_ge_u32 s12, s7
	v_mov_b32_e32 v42, 0
	v_mov_b32_e32 v45, 0
	v_mov_b32_e32 v47, 0
	s_cbranch_scc1 .LBB0_1531
	v_readlane_b32 s12, v254, 3
	s_add_i32 s12, s6, s12
	s_ashr_i32 s13, s12, 31
	s_lshl_b64 s[40:41], s[12:13], 10
	v_mad_i64_i32 v[10:11], s[12:13], s12, v227, v[4:5]
	v_lshl_add_u64 v[8:9], v[2:3], 0, s[40:41]
	global_load_ushort v88, v[10:11], off
	global_load_ushort v89, v[10:11], off offset:128
	global_load_ushort v90, v[10:11], off offset:256
	s_nop 0
	global_load_ushort v91, v[10:11], off offset:384
	s_nop 0
	global_load_dword v44, v[8:9], off
	global_load_dword v43, v[8:9], off offset:256
	global_load_dword v41, v[8:9], off offset:512
	global_load_dword v38, v[8:9], off offset:768
.LBB0_1531:
	v_readlane_b32 s12, v254, 4
	s_cmp_lt_u32 s12, s7
	v_mov_b32_e32 v24, 0
	s_cselect_b64 s[46:47], -1, 0
	s_cmp_ge_u32 s12, s7
	v_mov_b32_e32 v33, 0
	v_mov_b32_e32 v34, 0
	v_mov_b32_e32 v37, 0
	v_mov_b32_e32 v39, 0
	s_cbranch_scc1 .LBB0_1533
	v_readlane_b32 s12, v254, 4
	s_add_i32 s12, s6, s12
	s_ashr_i32 s13, s12, 31
	s_lshl_b64 s[40:41], s[12:13], 10
	v_mad_i64_i32 v[10:11], s[12:13], s12, v227, v[4:5]
	v_lshl_add_u64 v[8:9], v[2:3], 0, s[40:41]
	global_load_ushort v92, v[10:11], off
	global_load_ushort v93, v[10:11], off offset:128
	global_load_ushort v94, v[10:11], off offset:256
	s_nop 0
	global_load_ushort v95, v[10:11], off offset:384
	s_nop 0
	global_load_dword v36, v[8:9], off
	global_load_dword v35, v[8:9], off offset:256
	global_load_dword v32, v[8:9], off offset:512
	global_load_dword v30, v[8:9], off offset:768
.LBB0_1533:
	v_readlane_b32 s12, v254, 5
	s_cmp_lt_u32 s12, s7
	s_cselect_b64 s[44:45], -1, 0
	s_cmp_ge_u32 s12, s7
	v_mov_b32_e32 v26, 0
	v_mov_b32_e32 v29, 0
	v_mov_b32_e32 v31, 0
	s_cbranch_scc1 .LBB0_1535
	v_readlane_b32 s12, v254, 5
	s_add_i32 s12, s6, s12
	s_ashr_i32 s13, s12, 31
	s_lshl_b64 s[40:41], s[12:13], 10
	v_mad_i64_i32 v[10:11], s[12:13], s12, v227, v[4:5]
	v_lshl_add_u64 v[8:9], v[2:3], 0, s[40:41]
	global_load_ushort v96, v[10:11], off
	global_load_ushort v97, v[10:11], off offset:128
	global_load_ushort v98, v[10:11], off offset:256
	s_nop 0
	global_load_ushort v99, v[10:11], off offset:384
	s_nop 0
	global_load_dword v28, v[8:9], off
	global_load_dword v27, v[8:9], off offset:256
	global_load_dword v25, v[8:9], off offset:512
	global_load_dword v22, v[8:9], off offset:768
.LBB0_1535:
	s_waitcnt vmcnt(40)
	v_readlane_b32 s12, v254, 6
	s_cmp_lt_u32 s12, s7
	v_mov_b32_e32 v8, 0
	s_cselect_b64 s[42:43], -1, 0
	s_cmp_ge_u32 s12, s7
	v_mov_b32_e32 v17, 0
	v_mov_b32_e32 v18, 0
	v_mov_b32_e32 v21, 0
	v_mov_b32_e32 v23, 0
	s_cbranch_scc1 .LBB0_1537
	v_readlane_b32 s12, v254, 6
	s_add_i32 s12, s6, s12
	s_ashr_i32 s13, s12, 31
	s_lshl_b64 s[40:41], s[12:13], 10
	v_mad_i64_i32 v[12:13], s[12:13], s12, v227, v[4:5]
	v_lshl_add_u64 v[10:11], v[2:3], 0, s[40:41]
	global_load_ushort v100, v[12:13], off
	global_load_ushort v101, v[12:13], off offset:128
	global_load_ushort v102, v[12:13], off offset:256
	s_nop 0
	global_load_ushort v103, v[12:13], off offset:384
	s_nop 0
	global_load_dword v20, v[10:11], off
	global_load_dword v19, v[10:11], off offset:256
	global_load_dword v16, v[10:11], off offset:512
	global_load_dword v14, v[10:11], off offset:768
.LBB0_1537:
	v_readlane_b32 s12, v254, 7
	s_cmp_lt_u32 s12, s7
	s_cselect_b64 s[40:41], -1, 0
	s_cmp_ge_u32 s12, s7
	v_mov_b32_e32 v10, 0
	v_mov_b32_e32 v13, 0
	v_mov_b32_e32 v15, 0
	s_cbranch_scc1 .LBB0_1547
	v_readlane_b32 s7, v254, 7
	s_add_i32 s12, s6, s7
	s_ashr_i32 s13, s12, 31
	s_lshl_b64 s[82:83], s[12:13], 10
	v_mad_i64_i32 v[4:5], s[12:13], s12, v227, v[4:5]
	v_lshl_add_u64 v[2:3], v[2:3], 0, s[82:83]
	global_load_ushort v104, v[4:5], off
	global_load_ushort v105, v[4:5], off offset:128
	global_load_ushort v108, v[4:5], off offset:256
	s_nop 0
	global_load_ushort v109, v[4:5], off offset:384
	s_nop 0
	global_load_dword v12, v[2:3], off
	global_load_dword v11, v[2:3], off offset:256
	global_load_dword v9, v[2:3], off offset:512
	global_load_dword v7, v[2:3], off offset:768
	s_waitcnt vmcnt(0)
	v_lshlrev_b32_e32 v71, 16, v76
	v_lshlrev_b32_e32 v70, 16, v77
	v_lshlrev_b32_e32 v67, 16, v78
	v_lshlrev_b32_e32 v66, 16, v79
	v_lshlrev_b32_e32 v63, 16, v80
	v_lshlrev_b32_e32 v61, 16, v81
	v_lshlrev_b32_e32 v58, 16, v82
	v_lshlrev_b32_e32 v56, 16, v83
	v_lshlrev_b32_e32 v55, 16, v84
	v_lshlrev_b32_e32 v53, 16, v85
	v_lshlrev_b32_e32 v50, 16, v86
	v_lshlrev_b32_e32 v49, 16, v87
	v_lshlrev_b32_e32 v47, 16, v88
	v_lshlrev_b32_e32 v45, 16, v89
	v_lshlrev_b32_e32 v42, 16, v90
	v_lshlrev_b32_e32 v40, 16, v91
	v_lshlrev_b32_e32 v39, 16, v92
	v_lshlrev_b32_e32 v37, 16, v93
	v_lshlrev_b32_e32 v34, 16, v94
	v_lshlrev_b32_e32 v33, 16, v95
	v_lshlrev_b32_e32 v31, 16, v96
	v_lshlrev_b32_e32 v29, 16, v97
	v_lshlrev_b32_e32 v26, 16, v98
	v_lshlrev_b32_e32 v24, 16, v99
	v_lshlrev_b32_e32 v23, 16, v100
	v_lshlrev_b32_e32 v21, 16, v101
	v_lshlrev_b32_e32 v18, 16, v102
	v_lshlrev_b32_e32 v17, 16, v103
	v_lshlrev_b32_e32 v15, 16, v104
	v_lshlrev_b32_e32 v13, 16, v105
	v_lshlrev_b32_e32 v10, 16, v108
	v_lshlrev_b32_e32 v8, 16, v109
	s_andn2_b64 vcc, exec, s[38:39]
	v_lshl_add_u64 v[0:1], v[0:1], 1, s[28:29]
	s_cbranch_vccz .LBB0_1548

.LBB0_1547:
	s_waitcnt vmcnt(0)
	v_lshlrev_b32_e32 v71, 16, v76
	v_lshlrev_b32_e32 v70, 16, v77
	v_lshlrev_b32_e32 v67, 16, v78
	v_lshlrev_b32_e32 v66, 16, v79
	v_lshlrev_b32_e32 v63, 16, v80
	v_lshlrev_b32_e32 v61, 16, v81
	v_lshlrev_b32_e32 v58, 16, v82
	v_lshlrev_b32_e32 v56, 16, v83
	v_lshlrev_b32_e32 v55, 16, v84
	v_lshlrev_b32_e32 v53, 16, v85
	v_lshlrev_b32_e32 v50, 16, v86
	v_lshlrev_b32_e32 v49, 16, v87
	v_lshlrev_b32_e32 v47, 16, v88
	v_lshlrev_b32_e32 v45, 16, v89
	v_lshlrev_b32_e32 v42, 16, v90
	v_lshlrev_b32_e32 v40, 16, v91
	v_lshlrev_b32_e32 v39, 16, v92
	v_lshlrev_b32_e32 v37, 16, v93
	v_lshlrev_b32_e32 v34, 16, v94
	v_lshlrev_b32_e32 v33, 16, v95
	v_lshlrev_b32_e32 v31, 16, v96
	v_lshlrev_b32_e32 v29, 16, v97
	v_lshlrev_b32_e32 v26, 16, v98
	v_lshlrev_b32_e32 v24, 16, v99
	v_lshlrev_b32_e32 v23, 16, v100
	v_lshlrev_b32_e32 v21, 16, v101
	v_lshlrev_b32_e32 v18, 16, v102
	v_lshlrev_b32_e32 v17, 16, v103
	v_lshlrev_b32_e32 v15, 16, v104
	v_lshlrev_b32_e32 v13, 16, v105
	v_lshlrev_b32_e32 v10, 16, v108
	v_lshlrev_b32_e32 v8, 16, v109
	s_andn2_b64 vcc, exec, s[38:39]
	v_lshl_add_u64 v[0:1], v[0:1], 1, s[28:29]
	s_cbranch_vccnz .LBB0_1539
